# attention: softmax denominators accumulated on VALU (packed f32 adds of the exp outputs) instead of the ones-column MFMA
# baseline (speedup 1.0000x reference)
; __device__ __forceinline__ unsigned pk4_fp8(float a, float b, float c, float d) { int w = 0; w = __builtin_amdgcn_cvt_pk_fp8_f32(a, b, w, false); w = __builtin_amdgcn_cvt_pk_fp8_f32(c, d, w, true); return (unsigned)w; }
; #define SBAR() __builtin_amdgcn_sched_barrier(0)
; #define WBAR() do { asm volatile("s_waitcnt vmcnt(0) lgkmcnt(0)" ::: "memory"); __builtin_amdgcn_s_barrier(); asm volatile("" ::: "memory"); } while (0)
; __device__ __forceinline__ void finishSM(f32x16& p0, f32x16& p1, v8i& pa) {
; #pragma unroll
;     for (int r = 0; r < 16; ++r) p1[r] = __builtin_amdgcn_exp2f(p1[r]);
; #pragma unroll
;     for (int w = 0; w < 4; ++w) { pa[w] = (int)pk4_fp8(p0[4 * w], p0[4 * w + 1], p0[4 * w + 2], p0[4 * w + 3]); pa[4 + w] = (int)pk4_fp8(p1[4 * w], p1[4 * w + 1], p1[4 * w + 2], p1[4 * w + 3]); }
; }
; __device__ __forceinline__ void attn_unit(const unsigned char* __restrict__ Qb, const unsigned char* __restrict__ Kh, const unsigned char* __restrict__ VTh, f16* __restrict__ Ob, int seq, LAS char* lds) {
;     ...
;     f32x16 pA0, pA1, pB0, pB1; float dlA, dlB, alA, alB; v8i pa; const int NT = seq / 64;
;     const int NS = NT >> 1;
;     WBAR();
;     ISSUE(0);
;     WBAR();
;     if (1 < NS) ISSUE(1);
;     qkt(pA0, pA1, KSL(0), ka0, ka1, qf, negm); partialSM<true>(pA0, pA1, negm, dlA, alA);
;     for (int j = 1; j + 1 < NT; j += 2) {
;         SBAR(); qkt(pB0, pB1, KSL(j), ka0, ka1, qf, negm);
;         finishSM(pA0, pA1, pa); SBAR();
;         pv_d0(o, VSL(j - 1), va0, va1, pa); partialSM<false>(pB0, pB1, negm, dlB, alB);
;         WBAR();
;         { const int J = (j - 1) >> 1; if (J + 2 < NS) ISSUE(J + 2); }
;         FIX(alB, dlB, pB0, pB1);
;         SBAR(); qkt(pA0, pA1, KSL(j + 1), ka0, ka1, qf, negm);
;         finishSM(pB0, pB1, pa); SBAR();
;         pv_d0(o, VSL(j), va0, va1, pa); partialSM<false>(pA0, pA1, negm, dlA, alA);
;         FIX(alA, dlA, pA0, pA1);
;     }
;     SBAR(); qkt(pB0, pB1, KSL(NT - 1), ka0, ka1, qf, negm);
;     finishSM(pA0, pA1, pa); SBAR();
;     pv_d0(o, VSL(NT - 2), va0, va1, pa); partialSM<false>(pB0, pB1, negm, dlB, alB);
;     FIX(alB, dlB, pB0, pB1);
;     finishSM(pB0, pB1, pa); SBAR();
.LBB0_500:
	s_or_b64 exec, exec, s[0:1]
	s_waitcnt lgkmcnt(0)
	v_add_u32_e32 v115, s20, v242
	ds_read_b128 v[116:119], v115 offset:224
	ds_read_b128 v[120:123], v115 offset:192
	ds_read_b128 v[124:127], v115 offset:160
	ds_read_b128 v[128:131], v115 offset:128
	v_pk_add_f32 v[96:97], v[96:97], v[0:1] op_sel_hi:[1,0] neg_lo:[0,1] neg_hi:[0,1]
	s_waitcnt lgkmcnt(0)
	v_pk_mul_f32 v[76:77], v[76:77], v[116:117]
	v_pk_mul_f32 v[72:73], v[72:73], v[120:121]
	v_pk_mul_f32 v[68:69], v[68:69], v[124:125]
	v_pk_mul_f32 v[78:79], v[78:79], v[118:119]
	v_pk_mul_f32 v[74:75], v[74:75], v[122:123]
	v_pk_mul_f32 v[70:71], v[70:71], v[126:127]
	v_pk_mul_f32 v[66:67], v[66:67], v[130:131]
	v_pk_mul_f32 v[64:65], v[64:65], v[128:129]
	v_pk_mul_f32 v[60:61], v[60:61], v[116:117]
	v_pk_mul_f32 v[56:57], v[56:57], v[120:121]
	v_pk_mul_f32 v[52:53], v[52:53], v[124:125]
	v_pk_mul_f32 v[62:63], v[62:63], v[118:119]
	v_pk_mul_f32 v[58:59], v[58:59], v[122:123]
	v_pk_mul_f32 v[54:55], v[54:55], v[126:127]
	v_pk_mul_f32 v[50:51], v[50:51], v[130:131]
	v_pk_mul_f32 v[48:49], v[48:49], v[128:129]
	v_pk_mul_f32 v[44:45], v[44:45], v[116:117]
	v_pk_mul_f32 v[40:41], v[40:41], v[120:121]
	v_pk_mul_f32 v[36:37], v[36:37], v[124:125]
	v_pk_mul_f32 v[46:47], v[46:47], v[118:119]
	v_pk_mul_f32 v[42:43], v[42:43], v[122:123]
	v_pk_mul_f32 v[38:39], v[38:39], v[126:127]
	v_pk_mul_f32 v[34:35], v[34:35], v[130:131]
	v_pk_mul_f32 v[32:33], v[32:33], v[128:129]
	v_pk_mul_f32 v[28:29], v[28:29], v[116:117]
	v_pk_mul_f32 v[24:25], v[24:25], v[120:121]
	v_pk_mul_f32 v[20:21], v[20:21], v[124:125]
	v_pk_mul_f32 v[30:31], v[30:31], v[118:119]
	v_pk_mul_f32 v[26:27], v[26:27], v[122:123]
	v_pk_mul_f32 v[22:23], v[22:23], v[126:127]
	v_pk_mul_f32 v[18:19], v[18:19], v[130:131]
	v_pk_mul_f32 v[16:17], v[16:17], v[128:129]
	v_pk_mul_f32 v[80:81], v[80:81], v[114:115] op_sel_hi:[1,0]
	v_pk_mul_f32 v[82:83], v[82:83], v[114:115] op_sel_hi:[1,0]
	v_pk_add_f32 v[98:99], v[98:99], v[0:1] op_sel_hi:[1,0] neg_lo:[0,1] neg_hi:[0,1]
	v_pk_add_f32 v[100:101], v[100:101], v[0:1] op_sel_hi:[1,0] neg_lo:[0,1] neg_hi:[0,1]
	v_pk_add_f32 v[102:103], v[102:103], v[0:1] op_sel_hi:[1,0] neg_lo:[0,1] neg_hi:[0,1]
	v_pk_add_f32 v[104:105], v[104:105], v[0:1] op_sel_hi:[1,0] neg_lo:[0,1] neg_hi:[0,1]
	v_pk_add_f32 v[106:107], v[106:107], v[0:1] op_sel_hi:[1,0] neg_lo:[0,1] neg_hi:[0,1]
	v_pk_add_f32 v[108:109], v[108:109], v[0:1] op_sel_hi:[1,0] neg_lo:[0,1] neg_hi:[0,1]
	v_pk_mul_f32 v[4:5], v[4:5], v[114:115] op_sel_hi:[1,0]
	v_pk_mul_f32 v[6:7], v[6:7], v[114:115] op_sel_hi:[1,0]
	v_pk_mul_f32 v[2:3], v[2:3], v[114:115] op_sel_hi:[1,0]
	v_pk_mul_f32 v[10:11], v[10:11], v[114:115] op_sel_hi:[1,0]
	v_pk_mul_f32 v[12:13], v[12:13], v[114:115] op_sel_hi:[1,0]
	v_pk_mul_f32 v[112:113], v[112:113], v[114:115] op_sel_hi:[1,0]
	v_pk_mul_f32 v[8:9], v[8:9], v[114:115] op_sel_hi:[1,0]
	v_pk_mul_f32 v[14:15], v[14:15], v[114:115] op_sel_hi:[1,0]
	v_pk_add_f32 v[110:111], v[110:111], v[0:1] op_sel_hi:[1,0] neg_lo:[0,1] neg_hi:[0,1]
.LBB0_501:
	v_exp_f32_e32 v0, v96
	v_exp_f32_e32 v97, v97
	v_exp_f32_e32 v114, v100
	v_exp_f32_e32 v115, v101
	v_mov_b32_e32 v100, v1
	v_mov_b32_e32 v101, v1
	v_exp_f32_e32 v98, v98
	v_exp_f32_e32 v99, v99
	v_exp_f32_e32 v102, v102
	v_exp_f32_e32 v103, v103
	v_add_f32_e32 v80, v80, v0
	v_add_f32_e32 v82, v82, v97
	v_cvt_pk_fp8_f32 v100, v0, v97
	v_add_f32_e32 v80, v80, v114
	v_add_f32_e32 v82, v82, v115
	v_cvt_pk_fp8_f32 v101, v114, v115
	v_exp_f32_e32 v104, v104
	v_exp_f32_e32 v105, v105
	v_exp_f32_e32 v108, v108
	v_exp_f32_e32 v109, v109
	s_add_i32 s47, s47, -1
	v_mov_b32_e32 v96, v1
	v_mov_b32_e32 v97, v1
	v_add_f32_e32 v80, v80, v98
	v_add_f32_e32 v82, v82, v99
	v_cvt_pk_fp8_f32 v100, v98, v99 op_sel:[0,0,1]
	v_add_f32_e32 v80, v80, v102
	v_add_f32_e32 v82, v82, v103
	v_cvt_pk_fp8_f32 v101, v102, v103 op_sel:[0,0,1]
	v_mov_b32_e32 v98, v1
	v_mov_b32_e32 v102, v1
	v_mov_b32_e32 v99, v1
	v_mov_b32_e32 v103, v1
	s_lshr_b32 s2, s47, 1
	s_lshl_b64 s[0:1], s[88:89], 11
	v_readlane_b32 s4, v255, 10
	v_exp_f32_e32 v106, v106
	v_exp_f32_e32 v107, v107
	v_exp_f32_e32 v110, v110
	v_exp_f32_e32 v111, v111
	v_cvt_pk_fp8_f32 v96, v14, v15
	v_cvt_pk_fp8_f32 v97, v112, v113
	v_cvt_pk_fp8_f32 v98, v10, v11
	v_add_f32_e32 v80, v80, v104
	v_add_f32_e32 v82, v82, v105
	v_cvt_pk_fp8_f32 v102, v104, v105
	v_cvt_pk_fp8_f32 v99, v6, v7
	v_add_f32_e32 v80, v80, v108
	v_add_f32_e32 v82, v82, v109
	v_cvt_pk_fp8_f32 v103, v108, v109
	v_readlane_b32 s5, v255, 11
	s_add_u32 s0, s4, s0
	s_addc_u32 s1, s5, s1
	s_lshl_b32 s3, s6, 8
	s_add_u32 s3, s0, s3
	v_cvt_pk_fp8_f32 v96, v8, v9 op_sel:[0,0,1]
	v_cvt_pk_fp8_f32 v97, v12, v13 op_sel:[0,0,1]
	v_cvt_pk_fp8_f32 v98, v2, v3 op_sel:[0,0,1]
	v_add_f32_e32 v80, v80, v106
	v_add_f32_e32 v82, v82, v107
	v_cvt_pk_fp8_f32 v102, v106, v107 op_sel:[0,0,1]
	v_cvt_pk_fp8_f32 v99, v4, v5 op_sel:[0,0,1]
	v_add_f32_e32 v80, v80, v110
	v_add_f32_e32 v82, v82, v111
	v_cvt_pk_fp8_f32 v103, v110, v111 op_sel:[0,0,1]
	s_addc_u32 s4, s1, 0
	s_mul_hi_u32 s0, s2, 0x55555556
	s_mul_i32 s0, s0, 3
	s_sub_i32 s0, s2, s0
	s_lshl_b32 s0, s0, 14
	s_add_i32 s0, s0, 0
	v_add_u32_e32 v0, s0, v241
	v_add_u32_e32 v10, s0, v240
	ds_read_b128 v[2:5], v0 offset:8192
	ds_read_b128 v[6:9], v10 offset:8192
	v_mov_b32_e32 v161, v160
	v_mov_b32_e32 v162, v160
	v_mov_b32_e32 v163, v160
	s_waitcnt lgkmcnt(0)
	v_mfma_scale_f32_32x32x64_f8f6f4 v[64:79], v[96:103], v[2:9], v[64:79], v234, v234 op_sel_hi:[0,0,0]
	ds_read_b128 v[2:5], v0 offset:10240
	ds_read_b128 v[6:9], v10 offset:10240
	v_mov_b32_e32 v164, v160
	v_mov_b32_e32 v165, v160
	v_mov_b32_e32 v166, v160
	v_mov_b32_e32 v167, v160
	v_readlane_b32 s0, v255, 17
	v_readlane_b32 s1, v255, 18
	s_ashr_i32 s1, s0, 31
	s_lshl_b64 s[0:1], s[0:1], 11
	s_add_u32 s0, s3, s0
	s_addc_u32 s1, s4, s1
	s_waitcnt lgkmcnt(0)
; #define LAS __attribute__((address_space(3)))
; #define SBAR() __builtin_amdgcn_sched_barrier(0)
; #define MFMA8(A, B, C) __builtin_amdgcn_mfma_scale_f32_32x32x64_f8f6f4(A, B, C, 0, 0, 0, 0x7F7F7F7F, 0, 0x7F7F7F7F)
; __device__ __forceinline__ v8i ld32(const LAS char* a0, const LAS char* a1) { const v4i x = *(const LAS v4i*)a0, y = *(const LAS v4i*)a1; return (v8i){x[0], x[1], x[2], x[3], y[0], y[1], y[2], y[3]}; }
; __device__ __forceinline__ void pv_d0(f32x16* o, const LAS char* Vs, int va0, int va1, v8i pa) {
; #pragma unroll
;     for (int d0 = 0; d0 < 4; ++d0) { const v8i vf = ld32(Vs + va0 + 2048 * d0, Vs + va1 + 2048 * d0); o[d0] = MFMA8(pa, vf, o[d0]); }
;     const v8i ones = {0x38383838, 0x38383838, 0x38383838, 0x38383838, 0x38383838, 0x38383838, 0x38383838, 0x38383838};
;     o[4] = MFMA8(pa, ones, o[4]);
; }
; __device__ __forceinline__ void attn_unit(const unsigned char* __restrict__ Qb, const unsigned char* __restrict__ Kh, const unsigned char* __restrict__ VTh, f16* __restrict__ Ob, int seq, LAS char* lds) {
;     ...
;     finishSM(pB0, pB1, pa); SBAR();
;     pv_d0(o, VSL(NT - 1), va0, va1, pa);
;     float rli[16];
; #pragma unroll
;     for (int r = 0; r < 16; ++r) rli[r] = __builtin_amdgcn_rcpf(o[4][r]);
	v_mfma_scale_f32_32x32x64_f8f6f4 v[48:63], v[96:103], v[2:9], v[48:63], v234, v234 op_sel_hi:[0,0,0]
	ds_read_b128 v[2:5], v0 offset:12288
	ds_read_b128 v[6:9], v10 offset:12288
	s_waitcnt lgkmcnt(0)
	v_mfma_scale_f32_32x32x64_f8f6f4 v[32:47], v[96:103], v[2:9], v[32:47], v234, v234 op_sel_hi:[0,0,0]
	ds_read_b128 v[2:5], v0 offset:14336
	ds_read_b128 v[6:9], v10 offset:14336
	v_lshlrev_b32_e32 v0, 1, v238
	v_pk_add_f32 v[80:81], v[80:81], v[82:83]
	v_add_f32_e32 v80, v80, v81
	v_mov_b32_e32 v81, v80
	s_nop 1
	v_permlane32_swap_b32_e32 v80, v81
	v_add_f32_e32 v80, v80, v81
	s_and_saveexec_b64 vcc, s[12:13]
	ds_write_b32 v243, v80 offset:128
	s_or_b64 exec, exec, vcc
	s_waitcnt lgkmcnt(0)
	v_add_u32_e32 v84, s20, v242
	ds_read_b128 v[80:83], v84 offset:128
	ds_read_b128 v[88:91], v84 offset:192
	ds_read_b128 v[92:95], v84 offset:224
	ds_read_b128 v[84:87], v84 offset:160
	s_waitcnt lgkmcnt(0)
	s_nop 14
	v_rcp_f32_e32 v10, v84
	v_rcp_f32_e32 v11, v85
	v_rcp_f32_e32 v12, v86
	v_rcp_f32_e32 v13, v87
	v_rcp_f32_e32 v14, v88
	v_rcp_f32_e32 v15, v89
	v_rcp_f32_e32 v84, v94
	v_rcp_f32_e32 v85, v95
	s_waitcnt lgkmcnt(0)
; __device__ __forceinline__ int crow(int r, int hi) { return (r & 3) + 8 * (r >> 2) + 4 * hi; }
; __device__ __forceinline__ void attn_unit(const unsigned char* __restrict__ Qb, const unsigned char* __restrict__ Kh, const unsigned char* __restrict__ VTh, f16* __restrict__ Ob, int seq, LAS char* lds) {
;     ...
;     float rli[16];
; #pragma unroll
;     for (int r = 0; r < 16; ++r) rli[r] = __builtin_amdgcn_rcpf(o[4][r]);
;     f16* Ow = Ob + (long)(wid * 32) * LDC;
; #pragma unroll
;     for (int r = 0; r < 16; ++r) { const int orow = crow(r, hi);
; #pragma unroll
;         for (int d0 = 0; d0 < 4; ++d0) Ow[(long)orow * LDC + d0 * 32 + r32] = (f16)(o[d0][r] * rli[r]); }
	v_mfma_scale_f32_32x32x64_f8f6f4 v[16:31], v[96:103], v[2:9], v[16:31], v234, v234 op_sel_hi:[0,0,0]
	v_rcp_f32_e32 v6, v80
	v_lshlrev_b32_e32 v2, 13, v239
	v_lshl_add_u64 v[4:5], s[0:1], 0, v[0:1]
	v_mov_b32_e32 v3, v1
	v_rcp_f32_e32 v7, v81
	v_lshl_add_u64 v[2:3], v[4:5], 0, v[2:3]
	v_fma_mixlo_f16 v0, v64, v6, 0
	flat_store_short v[2:3], v0 offset:1024
	v_fma_mixlo_f16 v0, v48, v6, 0
	flat_store_short v[2:3], v0 offset:1088
	v_fma_mixlo_f16 v0, v32, v6, 0
	flat_store_short v[2:3], v0 offset:1152
	v_rcp_f32_e32 v8, v82
	s_movk_i32 s0, 0x1000
	v_add_co_u32_e32 v4, vcc, s0, v2
	s_nop 4
	v_fma_mixlo_f16 v0, v16, v6, 0
	flat_store_short v[2:3], v0 offset:1216
	v_fma_mixlo_f16 v0, v65, v7, 0
	flat_store_short v[2:3], v0 offset:3072
	v_fma_mixlo_f16 v0, v49, v7, 0
	flat_store_short v[2:3], v0 offset:3136
	v_fma_mixlo_f16 v0, v33, v7, 0
	flat_store_short v[2:3], v0 offset:3200
	v_fma_mixlo_f16 v0, v17, v7, 0
	v_rcp_f32_e32 v9, v83
	flat_store_short v[2:3], v0 offset:3264
	v_fma_mixlo_f16 v0, v66, v8, 0
	v_addc_co_u32_e32 v5, vcc, 0, v3, vcc
	flat_store_short v[4:5], v0 offset:1024
	v_fma_mixlo_f16 v0, v50, v8, 0
	flat_store_short v[4:5], v0 offset:1088
	v_fma_mixlo_f16 v0, v34, v8, 0
	flat_store_short v[4:5], v0 offset:1152
	v_fma_mixlo_f16 v0, v18, v8, 0
	flat_store_short v[4:5], v0 offset:1216
	v_fma_mixlo_f16 v0, v67, v9, 0
	flat_store_short v[4:5], v0 offset:3072
	v_fma_mixlo_f16 v0, v51, v9, 0
	flat_store_short v[4:5], v0 offset:3136
	v_fma_mixlo_f16 v0, v35, v9, 0
	flat_store_short v[4:5], v0 offset:3200
	v_fma_mixlo_f16 v0, v19, v9, 0
	flat_store_short v[4:5], v0 offset:3264
	v_add_co_u32_e32 v4, vcc, s63, v2
	v_fma_mixlo_f16 v0, v68, v10, 0
	s_nop 0
	v_addc_co_u32_e32 v5, vcc, 0, v3, vcc
	flat_store_short v[4:5], v0 offset:1024
	v_fma_mixlo_f16 v0, v52, v10, 0
	flat_store_short v[4:5], v0 offset:1088
	v_fma_mixlo_f16 v0, v36, v10, 0
	flat_store_short v[4:5], v0 offset:1152
	v_fma_mixlo_f16 v0, v20, v10, 0
	flat_store_short v[4:5], v0 offset:1216
	v_fma_mixlo_f16 v0, v69, v11, 0
	flat_store_short v[4:5], v0 offset:3072
	v_fma_mixlo_f16 v0, v53, v11, 0
	flat_store_short v[4:5], v0 offset:3136
	v_fma_mixlo_f16 v0, v37, v11, 0
	flat_store_short v[4:5], v0 offset:3200
	v_fma_mixlo_f16 v0, v21, v11, 0
	s_movk_i32 s0, 0x5000
	flat_store_short v[4:5], v0 offset:3264
	v_add_co_u32_e32 v4, vcc, s0, v2
	v_fma_mixlo_f16 v0, v70, v12, 0
	s_nop 0
	v_addc_co_u32_e32 v5, vcc, 0, v3, vcc
	flat_store_short v[4:5], v0 offset:1024
	v_fma_mixlo_f16 v0, v54, v12, 0
	flat_store_short v[4:5], v0 offset:1088
	v_fma_mixlo_f16 v0, v38, v12, 0
	flat_store_short v[4:5], v0 offset:1152
	v_fma_mixlo_f16 v0, v22, v12, 0
	flat_store_short v[4:5], v0 offset:1216
	v_fma_mixlo_f16 v0, v71, v13, 0
	flat_store_short v[4:5], v0 offset:3072
	v_fma_mixlo_f16 v0, v55, v13, 0
	flat_store_short v[4:5], v0 offset:3136
	v_fma_mixlo_f16 v0, v39, v13, 0
	flat_store_short v[4:5], v0 offset:3200
	v_fma_mixlo_f16 v0, v23, v13, 0
	s_mov_b32 s0, 0x8000
	flat_store_short v[4:5], v0 offset:3264
	v_add_co_u32_e32 v4, vcc, s0, v2
	v_fma_mixlo_f16 v0, v72, v14, 0
	s_nop 0
	v_addc_co_u32_e32 v5, vcc, 0, v3, vcc
	flat_store_short v[4:5], v0 offset:1024
	v_fma_mixlo_f16 v0, v56, v14, 0
	flat_store_short v[4:5], v0 offset:1088
	v_fma_mixlo_f16 v0, v40, v14, 0
	flat_store_short v[4:5], v0 offset:1152
	v_fma_mixlo_f16 v0, v24, v14, 0
	flat_store_short v[4:5], v0 offset:1216
	v_fma_mixlo_f16 v0, v73, v15, 0
	v_rcp_f32_e32 v80, v90
	flat_store_short v[4:5], v0 offset:3072
	v_fma_mixlo_f16 v0, v57, v15, 0
	flat_store_short v[4:5], v0 offset:3136
	v_fma_mixlo_f16 v0, v41, v15, 0
	flat_store_short v[4:5], v0 offset:3200
	v_fma_mixlo_f16 v0, v25, v15, 0
	s_mov_b32 s0, 0x9000
	flat_store_short v[4:5], v0 offset:3264
	v_add_co_u32_e32 v4, vcc, s0, v2
	v_rcp_f32_e32 v81, v91
	v_fma_mixlo_f16 v0, v74, v80, 0
	v_addc_co_u32_e32 v5, vcc, 0, v3, vcc
	flat_store_short v[4:5], v0 offset:1024
	v_fma_mixlo_f16 v0, v58, v80, 0
	flat_store_short v[4:5], v0 offset:1088
	v_fma_mixlo_f16 v0, v42, v80, 0
	flat_store_short v[4:5], v0 offset:1152
	v_fma_mixlo_f16 v0, v26, v80, 0
	flat_store_short v[4:5], v0 offset:1216
	v_fma_mixlo_f16 v0, v75, v81, 0
	v_rcp_f32_e32 v82, v92
	flat_store_short v[4:5], v0 offset:3072
	v_fma_mixlo_f16 v0, v59, v81, 0
	flat_store_short v[4:5], v0 offset:3136
	v_fma_mixlo_f16 v0, v43, v81, 0
	flat_store_short v[4:5], v0 offset:3200
	v_fma_mixlo_f16 v0, v27, v81, 0
	s_mov_b32 s0, 0xc000
	flat_store_short v[4:5], v0 offset:3264
	v_add_co_u32_e32 v4, vcc, s0, v2
	v_rcp_f32_e32 v83, v93
	v_fma_mixlo_f16 v0, v76, v82, 0
	v_addc_co_u32_e32 v5, vcc, 0, v3, vcc
	flat_store_short v[4:5], v0 offset:1024
	v_fma_mixlo_f16 v0, v60, v82, 0
	flat_store_short v[4:5], v0 offset:1088
	v_fma_mixlo_f16 v0, v44, v82, 0
	flat_store_short v[4:5], v0 offset:1152
	v_fma_mixlo_f16 v0, v28, v82, 0
	flat_store_short v[4:5], v0 offset:1216
	v_fma_mixlo_f16 v0, v77, v83, 0
	flat_store_short v[4:5], v0 offset:3072
	v_fma_mixlo_f16 v0, v61, v83, 0
	flat_store_short v[4:5], v0 offset:3136
	v_fma_mixlo_f16 v0, v45, v83, 0
	s_mov_b32 s0, 0xd000
	flat_store_short v[4:5], v0 offset:3200
	v_fma_mixlo_f16 v0, v29, v83, 0
	v_add_co_u32_e32 v2, vcc, s0, v2
	flat_store_short v[4:5], v0 offset:3264
	v_fma_mixlo_f16 v0, v78, v84, 0
	v_addc_co_u32_e32 v3, vcc, 0, v3, vcc
	flat_store_short v[2:3], v0 offset:1024
	v_fma_mixlo_f16 v0, v62, v84, 0
	flat_store_short v[2:3], v0 offset:1088
	v_fma_mixlo_f16 v0, v46, v84, 0
	flat_store_short v[2:3], v0 offset:1152
	v_fma_mixlo_f16 v0, v30, v84, 0
	flat_store_short v[2:3], v0 offset:1216
	v_fma_mixlo_f16 v0, v79, v85, 0
	flat_store_short v[2:3], v0 offset:3072
	v_fma_mixlo_f16 v0, v63, v85, 0
	v_readlane_b32 s0, v254, 18
	flat_store_short v[2:3], v0 offset:3136
	v_fma_mixlo_f16 v0, v47, v85, 0
	s_add_i32 s23, s23, s0
	flat_store_short v[2:3], v0 offset:3200
	v_fma_mixlo_f16 v0, v31, v85, 0
	s_cmpk_gt_i32 s23, 0x1ff
	flat_store_short v[2:3], v0 offset:3264
	v_readlane_b32 s1, v254, 19
	s_cbranch_scc1 .LBB0_422

; #define LAS __attribute__((address_space(3)))
; __device__ __forceinline__ v8i ld32(const LAS char* a0, const LAS char* a1) { const v4i x = *(const LAS v4i*)a0, y = *(const LAS v4i*)a1; return (v8i){x[0], x[1], x[2], x[3], y[0], y[1], y[2], y[3]}; }
; #define MFMA8QK(A, B, C) __builtin_amdgcn_mfma_scale_f32_32x32x64_f8f6f4(A, B, C, 0, 0, 0, 0x7F7F7F7F, 0, 0x7C7C7C7C)
; #define WBAR() do { asm volatile("s_waitcnt vmcnt(0) lgkmcnt(0)" ::: "memory"); __builtin_amdgcn_s_barrier(); asm volatile("" ::: "memory"); } while (0)
; __device__ __forceinline__ void qkt(f32x16& p0, f32x16& p1, const LAS char* Ks, int ka0, int ka1, const v8i* qf, const f32x16& negm) {
; #pragma unroll
;     for (int st = 0; st < 3; ++st) {
;         const v8i k0 = ld32(Ks + ka0 + 64 * st, Ks + ka1 + 64 * st), k1 = ld32(Ks + ka0 + 64 * st + 32 * 192, Ks + ka1 + 64 * st + 32 * 192);
;         if (st == 0) { p0 = MFMA8QK(k0, qf[st], negm); p1 = MFMA8QK(k1, qf[st], negm); }
;         else { p0 = MFMA8QK(k0, qf[st], p0); p1 = MFMA8QK(k1, qf[st], p1); } }
; __device__ __forceinline__ void attn_unit(const unsigned char* __restrict__ Qb, const unsigned char* __restrict__ Kh, const unsigned char* __restrict__ VTh, f16* __restrict__ Ob, int seq, LAS char* lds) {
;     ...
;     const int sw = (r32 >> 2) & 3;
;     const int ka0 = r32 * 192 + (((2 * hi) ^ sw) << 4), ka1 = r32 * 192 + (((2 * hi + 1) ^ sw) << 4);
;     const int va0 = r32 * 64 + (((2 * hi) ^ sw) << 4), va1 = r32 * 64 + (((2 * hi + 1) ^ sw) << 4);
;     ...
;     f32x16 pA0, pA1, pB0, pB1; float dlA, dlB, alA, alB; v8i pa; const int NT = seq / 64;
;     const int NS = NT >> 1;
;     WBAR();
;     ISSUE(0);
;     WBAR();
;     if (1 < NS) ISSUE(1);
;     qkt(pA0, pA1, KSL(0), ka0, ka1, qf, negm); partialSM<true>(pA0, pA1, negm, dlA, alA);
.LBB0_586:
	v_lshrrev_b32_e32 v0, 2, v2
	v_bfe_u32 v2, v2, 2, 2
	v_lshlrev_b32_e32 v3, 1, v239
	v_bitop3_b32 v0, v3, v0, 3 bitop3:0x78
	v_bitop3_b32 v2, v3, v2, 1 bitop3:0x36
	v_lshlrev_b32_e32 v0, 4, v0
	v_lshlrev_b32_e32 v58, 4, v2
	v_mul_u32_u24_e32 v2, 0xc0, v238
	v_or_b32_e32 v244, v0, v2
	s_add_i32 m0, s15, 0
	v_or_b32_e32 v245, v58, v2
	global_load_lds_dwordx4 v4, s[0:1]
	v_add_u32_e32 v59, 0, v244
	v_add_u32_e32 v60, 0, v245
	ds_read_b128 v[2:5], v59 offset:49152
	ds_read_b128 v[6:9], v60 offset:49152
	v_readlane_b32 s68, v253, 62
	v_readlane_b32 s69, v253, 63
	v_readlane_b32 s70, v254, 0
	v_readlane_b32 s71, v254, 1
	v_readlane_b32 s72, v254, 2
	v_readlane_b32 s73, v254, 3
	v_readlane_b32 s74, v254, 4
	v_readlane_b32 s75, v254, 5
	v_readlane_b32 s76, v254, 6
	v_readlane_b32 s77, v254, 7
	v_readlane_b32 s78, v254, 8
	v_readlane_b32 s79, v254, 9
	v_readlane_b32 s80, v254, 10
	v_readlane_b32 s81, v254, 11
	v_readlane_b32 s82, v254, 12
	v_readlane_b32 s83, v254, 13
	s_mov_b32 s69, s68
	s_mov_b32 s70, s68
	s_mov_b32 s71, s68
	s_mov_b32 s72, s68
	s_mov_b32 s73, s68
	s_mov_b32 s74, s68
	s_mov_b32 s75, s68
	s_mov_b32 s76, s68
	s_mov_b32 s77, s68
	s_mov_b32 s78, s68
	s_mov_b32 s79, s68
	s_mov_b32 s80, s68
	s_mov_b32 s81, s68
	s_mov_b32 s82, s68
	s_mov_b32 s83, s68
	v_mov_b64_e32 v[18:19], s[68:69]
	v_mov_b64_e32 v[20:21], s[70:71]
	v_mov_b64_e32 v[22:23], s[72:73]
	v_mov_b64_e32 v[24:25], s[74:75]
	v_mov_b64_e32 v[26:27], s[76:77]
	v_mov_b64_e32 v[28:29], s[78:79]
	v_mov_b64_e32 v[30:31], s[80:81]
	v_mov_b64_e32 v[32:33], s[82:83]
	ds_read_b128 v[34:37], v59 offset:49216
	ds_read_b128 v[38:41], v60 offset:49216
	s_waitcnt vmcnt(0) lgkmcnt(0)
	v_mfma_scale_f32_32x32x64_f8f6f4 v[2:17], v[2:9], v[184:191], v[18:33], v234, v233 op_sel_hi:[0,0,0]
	ds_read_b128 v[46:49], v60 offset:55296
	ds_read_b128 v[42:45], v59 offset:55296
	ds_read_b128 v[50:53], v59 offset:49280
	ds_read_b128 v[54:57], v60 offset:49280
	s_mov_b32 s0, s68
	v_writelane_b32 v253, s0, 62
	s_lshl_b32 s28, s2, 13
	s_add_i32 s28, s28, s17
	v_writelane_b32 v254, s2, 0
	v_writelane_b32 v254, s3, 1
	v_writelane_b32 v254, s4, 2
	v_writelane_b32 v254, s5, 3
	v_writelane_b32 v254, s6, 4
	v_writelane_b32 v254, s7, 5
	v_writelane_b32 v254, s8, 6
	v_writelane_b32 v254, s9, 7
	v_writelane_b32 v254, s10, 8
	v_writelane_b32 v254, s11, 9
	s_waitcnt lgkmcnt(2)
	v_mfma_scale_f32_32x32x64_f8f6f4 v[18:33], v[42:49], v[184:191], v[18:33], v234, v233 op_sel_hi:[0,0,0]
	v_writelane_b32 v254, s12, 10
	v_writelane_b32 v254, s13, 11
	v_writelane_b32 v254, s14, 12
	v_writelane_b32 v254, s15, 13
	s_and_b32 s0, s14, 0x3fffffc0
	s_lshl_b32 s0, s0, 2
	s_add_i32 s20, s0, 0
	s_lshl_b32 s0, s2, 12
	s_lshl_b32 s35, s16, 13
	s_add_i32 s29, s28, s0
	s_add_i32 s35, s35, s19
	s_lshl_b32 s0, s16, 12
	s_lshl_b32 s26, s18, 13
	s_lshl_b32 s22, s2, 6
	s_add_i32 s2, s35, s0
	v_mfma_scale_f32_32x32x64_f8f6f4 v[2:17], v[34:41], v[176:183], v[2:17], v234, v233 op_sel_hi:[0,0,0]
	ds_read_b128 v[38:41], v60 offset:55360
	ds_read_b128 v[34:37], v59 offset:55360
	ds_read_b128 v[42:45], v59 offset:55424
	ds_read_b128 v[46:49], v60 offset:55424
	s_add_i32 s26, s26, s46
	s_lshl_b32 s0, s18, 12
	s_lshl_b32 s31, s33, 13
	s_add_i32 s20, s20, 0x18000
	s_add_i32 s27, s26, s0
	s_add_i32 s31, s31, s50
	s_lshl_b32 s0, s33, 12
	v_or_b32_e32 v246, 0x3800, v58
	v_or_b32_e32 v248, 0x3000, v58
	v_or_b32_e32 v249, 0x2800, v58
	v_or_b32_e32 v250, 0x2000, v58
	v_or_b32_e32 v251, 0x3800, v0
	v_or_b32_e32 v252, 0x3000, v0
	v_or_b32_e32 v231, 0x2800, v0
	s_waitcnt lgkmcnt(2)
	v_mfma_scale_f32_32x32x64_f8f6f4 v[18:33], v[34:41], v[176:183], v[18:33], v234, v233 op_sel_hi:[0,0,0]
	v_lshlrev_b32_e32 v34, 6, v238
	v_or_b32_e32 v240, v58, v34
	v_or_b32_e32 v241, v0, v34
	v_add_u32_e32 v247, 0, v34
	v_or_b32_e32 v218, 0x2000, v0
	v_mov_b32_e32 v0, v1
	v_writelane_b32 v253, s1, 63
	s_mov_b32 s21, 2
	s_lshr_b32 s47, s3, 6
	s_lshr_b32 s14, s3, 7
	s_mov_b32 s15, 0
	v_cmp_eq_u32_e64 s[12:13], 0, v239
	v_lshl_add_u32 v243, v238, 2, s20
	v_lshlrev_b32_e32 v242, 4, v239
	s_lshl_b32 s34, s16, 6
	v_mfma_scale_f32_32x32x64_f8f6f4 v[2:17], v[50:57], v[168:175], v[2:17], v234, v233 op_sel_hi:[0,0,0]
	s_lshl_b32 s3, s18, 6
	s_lshl_b32 s30, s33, 6
	s_add_i32 s49, s31, s0
	s_lshl_b32 s16, s42, 6
	s_add_i32 s18, s38, s51
	s_add_i32 s33, s39, s51
	s_mov_b32 s68, 0xfffe5000
	s_mov_b32 s69, 0xfffe6000
	s_mov_b32 s70, 0xfffe7000
	s_mov_b32 s71, 0xfffe8000
	s_mov_b32 s72, 0xfffe9000
	s_mov_b32 s73, 0xfffea000
	s_mov_b32 s74, 0xfffeb000
	s_mov_b32 s75, 0xfffec000
	s_mov_b32 s76, 0xfffed000
	s_waitcnt lgkmcnt(0)
; #define WBAR() do { asm volatile("s_waitcnt vmcnt(0) lgkmcnt(0)" ::: "memory"); __builtin_amdgcn_s_barrier(); asm volatile("" ::: "memory"); } while (0)
; template <bool FIRST>
; __device__ __forceinline__ void partialSM(f32x16& p0, f32x16& p1, f32x16& negm, float& dl, float& alpha) {
;     float pmax = p0[0];
; #pragma unroll
;     for (int r = 1; r < 16; ++r) pmax = fmaxf(pmax, p0[r]);
; #pragma unroll
;     for (int r = 0; r < 16; ++r) pmax = fmaxf(pmax, p1[r]);
;     { auto rr = __builtin_amdgcn_permlane32_swap(__float_as_uint(pmax), __float_as_uint(pmax), false, false);
;       pmax = fmaxf(__uint_as_float(rr[0]), __uint_as_float(rr[1])); }
;     if (FIRST) {
;         dl = 0.f; alpha = 1.f; const float d0_ = pmax - SH;
; #pragma unroll
;         for (int r = 0; r < 16; ++r) { p0[r] -= d0_; p1[r] -= d0_; negm[r] -= d0_; }
;     } else {
;         const bool keep = __all(pmax <= SH + THRL);
;         dl = keep ? 0.f : fmaxf(pmax - SH, 0.f); alpha = __builtin_amdgcn_exp2f(-dl);
;     }
; #pragma unroll
;     for (int r = 0; r < 16; ++r) p0[r] = __builtin_amdgcn_exp2f(p0[r]);
; }
; __device__ __forceinline__ void attn_unit(const unsigned char* __restrict__ Qb, const unsigned char* __restrict__ Kh, const unsigned char* __restrict__ VTh, f16* __restrict__ Ob, int seq, LAS char* lds) {
;     ...
;     f32x16 pA0, pA1, pB0, pB1; float dlA, dlB, alA, alB; v8i pa; const int NT = seq / 64;
;     const int NS = NT >> 1;
;     WBAR();
;     ISSUE(0);
;     WBAR();
;     if (1 < NS) ISSUE(1);
	v_mfma_scale_f32_32x32x64_f8f6f4 v[18:33], v[42:49], v[168:175], v[18:33], v234, v233 op_sel_hi:[0,0,0]
	s_nop 2
	v_max_f32_e32 v35, v3, v3
	v_max_f32_e32 v36, v2, v2
	v_max_f32_e32 v35, v36, v35
	v_max3_f32 v35, v35, v4, v5
	v_max3_f32 v35, v35, v6, v7
	v_max3_f32 v35, v35, v8, v9
	v_max3_f32 v35, v35, v10, v11
	v_max3_f32 v35, v35, v12, v13
	v_max3_f32 v35, v35, v14, v15
	v_max3_f32 v35, v35, v16, v17
	s_mov_b32 s77, 0xfffee000
	s_mov_b32 s78, 0xfffef000
	s_mov_b32 s79, 0xffff0000
	s_mov_b32 s80, 0xffff1000
	s_mov_b32 s81, 0xffff2000
	s_nop 1
	v_max3_f32 v35, v35, v18, v19
	v_max3_f32 v35, v35, v20, v21
	v_max3_f32 v35, v35, v22, v23
	v_max3_f32 v35, v35, v24, v25
	v_max3_f32 v35, v35, v26, v27
	v_max3_f32 v35, v35, v28, v29
	v_max3_f32 v35, v35, v30, v31
	v_max3_f32 v35, v35, v32, v33
	v_mov_b32_e32 v36, v35
	s_nop 1
	v_permlane32_swap_b32_e32 v35, v36
	v_max_f32_e32 v36, v36, v36
	v_max_f32_e32 v35, v35, v35
	v_max_f32_e32 v35, v35, v36
	v_add_f32_e32 v35, -4.0, v35
	v_sub_f32_e32 v2, v2, v35
	v_exp_f32_e32 v228, v2
	v_sub_f32_e32 v2, v3, v35
	v_exp_f32_e32 v229, v2
	v_sub_f32_e32 v2, v4, v35
	v_exp_f32_e32 v220, v2
	v_sub_f32_e32 v2, v5, v35
	v_exp_f32_e32 v221, v2
	v_sub_f32_e32 v2, v6, v35
	v_exp_f32_e32 v226, v2
	v_sub_f32_e32 v2, v7, v35
	v_exp_f32_e32 v227, v2
	v_sub_f32_e32 v2, v8, v35
	v_exp_f32_e32 v224, v2
	v_sub_f32_e32 v2, v9, v35
	v_exp_f32_e32 v225, v2
	v_sub_f32_e32 v2, v10, v35
	v_exp_f32_e32 v222, v2
	v_sub_f32_e32 v2, v11, v35
	v_exp_f32_e32 v223, v2
	v_sub_f32_e32 v2, v12, v35
	v_exp_f32_e32 v162, v2
	v_sub_f32_e32 v2, v13, v35
	v_exp_f32_e32 v163, v2
	v_sub_f32_e32 v2, v14, v35
	v_exp_f32_e32 v166, v2
	v_sub_f32_e32 v2, v15, v35
	v_exp_f32_e32 v167, v2
	v_sub_f32_e32 v2, v16, v35
	v_exp_f32_e32 v164, v2
	v_sub_f32_e32 v2, v17, v35
	v_exp_f32_e32 v165, v2
	v_mov_b32_e32 v14, v1
	v_mov_b32_e32 v15, v1
	v_sub_f32_e32 v127, v33, v35
	v_sub_f32_e32 v126, v32, v35
	v_sub_f32_e32 v125, v31, v35
	v_sub_f32_e32 v124, v30, v35
	v_sub_f32_e32 v123, v29, v35
	v_sub_f32_e32 v122, v28, v35
	v_sub_f32_e32 v121, v27, v35
	v_sub_f32_e32 v120, v26, v35
	v_sub_f32_e32 v119, v25, v35
	v_sub_f32_e32 v118, v24, v35
	v_sub_f32_e32 v117, v23, v35
	v_sub_f32_e32 v116, v22, v35
	v_sub_f32_e32 v115, v21, v35
	v_sub_f32_e32 v114, v20, v35
	v_sub_f32_e32 v113, v19, v35
	v_sub_f32_e32 v112, v18, v35
	v_sub_f32_e32 v96, 4.0, v35
	v_mov_b32_e32 v2, v1
	v_mov_b32_e32 v3, v1
	v_mov_b32_e32 v4, v1
	v_mov_b32_e32 v5, v1
	v_mov_b32_e32 v6, v1
	v_mov_b32_e32 v7, v1
	v_mov_b32_e32 v8, v1
	v_mov_b32_e32 v9, v1
	v_mov_b32_e32 v10, v1
	v_mov_b32_e32 v11, v1
	v_mov_b32_e32 v12, v1
	v_mov_b32_e32 v13, v1
	v_mov_b64_e32 v[78:79], v[14:15]
	v_mov_b64_e32 v[62:63], v[14:15]
	v_mov_b64_e32 v[46:47], v[14:15]
	v_mov_b64_e32 v[30:31], v[14:15]
	v_mov_b64_e32 v[94:95], v[14:15]
	v_mov_b32_e32 v97, v96
	v_mov_b32_e32 v98, v96
	v_mov_b32_e32 v99, v96
	v_mov_b32_e32 v100, v96
	v_mov_b32_e32 v101, v96
	v_mov_b32_e32 v102, v96
	v_mov_b32_e32 v103, v96
	v_mov_b32_e32 v104, v96
	v_mov_b32_e32 v105, v96
	v_mov_b32_e32 v106, v96
	v_mov_b32_e32 v107, v96
	v_mov_b32_e32 v108, v96
	v_mov_b32_e32 v109, v96
	v_mov_b32_e32 v110, v96
	v_mov_b32_e32 v111, v96
	v_mov_b64_e32 v[76:77], v[12:13]
	v_mov_b64_e32 v[74:75], v[10:11]
	v_mov_b64_e32 v[72:73], v[8:9]
	v_mov_b64_e32 v[70:71], v[6:7]
	v_mov_b64_e32 v[68:69], v[4:5]
	v_mov_b64_e32 v[66:67], v[2:3]
	v_mov_b64_e32 v[64:65], v[0:1]
	v_mov_b64_e32 v[60:61], v[12:13]
	v_mov_b64_e32 v[58:59], v[10:11]
	v_mov_b64_e32 v[56:57], v[8:9]
	v_mov_b64_e32 v[54:55], v[6:7]
	v_mov_b64_e32 v[52:53], v[4:5]
	v_mov_b64_e32 v[50:51], v[2:3]
	v_mov_b64_e32 v[48:49], v[0:1]
	v_mov_b64_e32 v[44:45], v[12:13]
	v_mov_b64_e32 v[42:43], v[10:11]
	v_mov_b64_e32 v[40:41], v[8:9]
	v_mov_b64_e32 v[38:39], v[6:7]
	v_mov_b64_e32 v[36:37], v[4:5]
	v_mov_b64_e32 v[34:35], v[2:3]
	v_mov_b64_e32 v[32:33], v[0:1]
	v_mov_b64_e32 v[28:29], v[12:13]
	v_mov_b64_e32 v[26:27], v[10:11]
	v_mov_b64_e32 v[24:25], v[8:9]
	v_mov_b64_e32 v[22:23], v[6:7]
	v_mov_b64_e32 v[20:21], v[4:5]
	v_mov_b64_e32 v[18:19], v[2:3]
	v_mov_b64_e32 v[16:17], v[0:1]
	v_mov_b64_e32 v[92:93], v[12:13]
	v_mov_b64_e32 v[90:91], v[10:11]
	v_mov_b64_e32 v[88:89], v[8:9]
	v_mov_b64_e32 v[86:87], v[6:7]
	v_mov_b64_e32 v[84:85], v[4:5]
	v_mov_b64_e32 v[82:83], v[2:3]
	v_mov_b64_e32 v[80:81], v[0:1]
	v_lshlrev_b32_e32 v2, 4, v216
	v_and_b32_e32 v2, 0x3f0, v2
	v_or_b32_e32 v3, 0xffffe000, v2
	v_add_u32_e32 v4, s17, v3
	s_mov_b32 s0, 0xaaaaaaab
	v_mul_hi_u32 v5, v4, s0
	v_lshrrev_b32_e32 v6, 7, v5
	s_movk_i32 s0, 0xc0
	v_mul_lo_u32 v7, v6, s0
	v_add_u32_e32 v6, s22, v6
	s_movk_i32 s0, 0x300
	v_lshrrev_b32_e32 v5, 5, v5
	v_sub_u32_e32 v4, v4, v7
	v_mul_lo_u32 v6, v6, s0
	v_and_b32_e32 v5, 48, v5
	v_bitop3_b32 v4, v5, v6, v4 bitop3:0xde
	v_or_b32_e32 v8, s28, v2
	v_cndmask_b32_e64 v12, v8, v4, s[56:57]
	v_add_u32_e32 v4, s19, v3
	s_mov_b32 s0, 0xaaaaaaab
	v_mul_hi_u32 v5, v4, s0
	v_lshrrev_b32_e32 v6, 7, v5
	s_movk_i32 s0, 0xc0
	v_mul_lo_u32 v7, v6, s0
	v_add_u32_e32 v6, s34, v6
	s_movk_i32 s0, 0x300
	v_lshrrev_b32_e32 v5, 5, v5
	v_sub_u32_e32 v4, v4, v7
	v_mul_lo_u32 v6, v6, s0
	v_and_b32_e32 v5, 48, v5
	v_bitop3_b32 v4, v5, v6, v4 bitop3:0xde
	v_or_b32_e32 v8, s35, v2
	v_cndmask_b32_e64 v13, v4, v8, s[4:5]
	v_add_u32_e32 v4, s46, v3
	s_mov_b32 s0, 0xaaaaaaab
	v_mul_hi_u32 v5, v4, s0
	v_lshrrev_b32_e32 v6, 7, v5
	s_movk_i32 s0, 0xc0
	v_mul_lo_u32 v7, v6, s0
	v_add_u32_e32 v6, s3, v6
	s_movk_i32 s0, 0x300
	v_lshrrev_b32_e32 v5, 5, v5
	v_sub_u32_e32 v4, v4, v7
	v_mul_lo_u32 v6, v6, s0
	v_and_b32_e32 v5, 48, v5
	v_bitop3_b32 v4, v5, v6, v4 bitop3:0xde
	v_or_b32_e32 v8, s26, v2
	v_cndmask_b32_e64 v14, v4, v8, s[6:7]
	v_add_u32_e32 v4, s50, v3
	s_mov_b32 s0, 0xaaaaaaab
	v_mul_hi_u32 v5, v4, s0
	v_lshrrev_b32_e32 v6, 7, v5
	s_movk_i32 s0, 0xc0
	v_mul_lo_u32 v7, v6, s0
	v_add_u32_e32 v6, s30, v6
	s_movk_i32 s0, 0x300
	v_lshrrev_b32_e32 v5, 5, v5
	v_sub_u32_e32 v4, v4, v7
	v_mul_lo_u32 v6, v6, s0
	v_and_b32_e32 v5, 48, v5
	v_bitop3_b32 v4, v5, v6, v4 bitop3:0xde
	v_or_b32_e32 v8, s31, v2
	v_cndmask_b32_e64 v15, v4, v8, s[8:9]
	v_add_u32_e32 v4, s51, v3
	s_mov_b32 s0, 0xaaaaaaab
	v_mul_hi_u32 v5, v4, s0
	v_lshrrev_b32_e32 v6, 7, v5
	s_movk_i32 s0, 0xc0
	v_mul_lo_u32 v7, v6, s0
	v_add_u32_e32 v6, s16, v6
	s_movk_i32 s0, 0x300
	v_lshrrev_b32_e32 v5, 5, v5
	v_sub_u32_e32 v4, v4, v7
	v_mul_lo_u32 v6, v6, s0
	v_and_b32_e32 v5, 48, v5
	v_bitop3_b32 v4, v5, v6, v4 bitop3:0xde
	v_or_b32_e32 v8, s18, v2
	v_cndmask_b32_e64 v9, v4, v8, s[10:11]
	v_mov_b32_e32 v5, 0x19000
	v_lshl_add_u32 v6, v216, 4, v5
	v_lshl_add_u32 v7, v216, 2, v5
	ds_write_b128 v6, v[12:15]
	ds_write_b32 v7, v9 offset:8192
	s_bitcmp1_b32 s15, 0
	s_cselect_b32 s1, 0x6000, 0
	v_add_u32_e32 v12, s1, v244
	v_add_u32_e32 v13, s1, v245
	v_add_u32_e32 v14, 0xf000, v12
	v_add_u32_e32 v15, 0xf000, v13
	ds_read_b128 v[202:205], v12 offset:61440
	ds_read_b128 v[206:209], v13 offset:61440
	ds_read_b128 v[194:197], v14 offset:6144
	ds_read_b128 v[198:201], v15 offset:6144
	v_pk_add_f32 v[80:81], v[80:81], v[228:229]
	v_pk_add_f32 v[82:83], v[82:83], v[220:221]
	v_pk_add_f32 v[80:81], v[80:81], v[226:227]
	v_pk_add_f32 v[82:83], v[82:83], v[224:225]
	v_pk_add_f32 v[80:81], v[80:81], v[222:223]
	v_pk_add_f32 v[82:83], v[82:83], v[162:163]
	v_pk_add_f32 v[80:81], v[80:81], v[166:167]
	v_pk_add_f32 v[82:83], v[82:83], v[164:165]
	s_mov_b32 s82, 0xffff3000
	s_mov_b32 s83, 0xffff4000
	s_branch .LBB0_589
.LBB0_587:
	s_or_b64 exec, exec, s[0:1]
	s_waitcnt lgkmcnt(0)
	v_add_u32_e32 v3, s20, v242
	ds_read_b128 v[4:7], v3 offset:224
	ds_read_b128 v[8:11], v3 offset:192
	ds_read_b128 v[12:15], v3 offset:160
	ds_read_b128 v[128:131], v3 offset:128
	v_pk_mul_f32 v[164:165], v[164:165], v[0:1] op_sel_hi:[1,0]
	s_waitcnt lgkmcnt(0)
	v_pk_mul_f32 v[76:77], v[76:77], v[4:5]
	v_pk_mul_f32 v[72:73], v[72:73], v[8:9]
	v_pk_mul_f32 v[68:69], v[68:69], v[12:13]
	v_pk_mul_f32 v[78:79], v[78:79], v[6:7]
	v_pk_mul_f32 v[74:75], v[74:75], v[10:11]
	v_pk_mul_f32 v[70:71], v[70:71], v[14:15]
	v_pk_mul_f32 v[66:67], v[66:67], v[130:131]
	v_pk_mul_f32 v[64:65], v[64:65], v[128:129]
	v_pk_mul_f32 v[60:61], v[60:61], v[4:5]
	v_pk_mul_f32 v[56:57], v[56:57], v[8:9]
	v_pk_mul_f32 v[52:53], v[52:53], v[12:13]
	v_pk_mul_f32 v[62:63], v[62:63], v[6:7]
	v_pk_mul_f32 v[58:59], v[58:59], v[10:11]
	v_pk_mul_f32 v[54:55], v[54:55], v[14:15]
	v_pk_mul_f32 v[50:51], v[50:51], v[130:131]
	v_pk_mul_f32 v[48:49], v[48:49], v[128:129]
	v_pk_mul_f32 v[44:45], v[44:45], v[4:5]
	v_pk_mul_f32 v[40:41], v[40:41], v[8:9]
	v_pk_mul_f32 v[36:37], v[36:37], v[12:13]
	v_pk_mul_f32 v[46:47], v[46:47], v[6:7]
	v_pk_mul_f32 v[42:43], v[42:43], v[10:11]
	v_pk_mul_f32 v[38:39], v[38:39], v[14:15]
	v_pk_mul_f32 v[34:35], v[34:35], v[130:131]
	v_pk_mul_f32 v[32:33], v[32:33], v[128:129]
	v_pk_mul_f32 v[28:29], v[28:29], v[4:5]
	v_pk_mul_f32 v[24:25], v[24:25], v[8:9]
	v_pk_mul_f32 v[20:21], v[20:21], v[12:13]
	v_pk_mul_f32 v[30:31], v[30:31], v[6:7]
	v_pk_mul_f32 v[26:27], v[26:27], v[10:11]
	v_pk_mul_f32 v[22:23], v[22:23], v[14:15]
	v_pk_mul_f32 v[18:19], v[18:19], v[130:131]
	v_pk_mul_f32 v[16:17], v[16:17], v[128:129]
	v_pk_mul_f32 v[80:81], v[80:81], v[0:1] op_sel_hi:[1,0]
	v_pk_mul_f32 v[82:83], v[82:83], v[0:1] op_sel_hi:[1,0]
	v_pk_mul_f32 v[166:167], v[166:167], v[0:1] op_sel_hi:[1,0]
	v_pk_mul_f32 v[162:163], v[162:163], v[0:1] op_sel_hi:[1,0]
	v_pk_mul_f32 v[222:223], v[222:223], v[0:1] op_sel_hi:[1,0]
	v_pk_mul_f32 v[224:225], v[224:225], v[0:1] op_sel_hi:[1,0]
	v_pk_mul_f32 v[226:227], v[226:227], v[0:1] op_sel_hi:[1,0]
	v_pk_mul_f32 v[220:221], v[220:221], v[0:1] op_sel_hi:[1,0]
	v_pk_mul_f32 v[228:229], v[228:229], v[0:1] op_sel_hi:[1,0]
	v_sub_f32_e32 v127, v127, v2
	v_sub_f32_e32 v126, v126, v2
	v_sub_f32_e32 v125, v125, v2
	v_sub_f32_e32 v124, v124, v2
	v_sub_f32_e32 v123, v123, v2
	v_sub_f32_e32 v122, v122, v2
	v_sub_f32_e32 v121, v121, v2
	v_sub_f32_e32 v120, v120, v2
	v_sub_f32_e32 v119, v119, v2
	v_sub_f32_e32 v118, v118, v2
	v_sub_f32_e32 v117, v117, v2
	v_sub_f32_e32 v116, v116, v2
	v_sub_f32_e32 v115, v115, v2
	v_sub_f32_e32 v114, v114, v2
	v_sub_f32_e32 v113, v113, v2
	v_sub_f32_e32 v112, v112, v2
	v_sub_f32_e32 v111, v111, v2
	v_sub_f32_e32 v110, v110, v2
	v_sub_f32_e32 v109, v109, v2
	v_sub_f32_e32 v108, v108, v2
	v_sub_f32_e32 v107, v107, v2
	v_sub_f32_e32 v106, v106, v2
	v_sub_f32_e32 v105, v105, v2
	v_sub_f32_e32 v104, v104, v2
	v_sub_f32_e32 v103, v103, v2
	v_sub_f32_e32 v102, v102, v2
	v_sub_f32_e32 v101, v101, v2
	v_sub_f32_e32 v100, v100, v2
	v_sub_f32_e32 v99, v99, v2
	v_sub_f32_e32 v98, v98, v2
	v_sub_f32_e32 v97, v97, v2
	v_sub_f32_e32 v96, v96, v2

; #define LAS __attribute__((address_space(3)))
; #define SBAR() __builtin_amdgcn_sched_barrier(0)
; #define MFMA8(A, B, C) __builtin_amdgcn_mfma_scale_f32_32x32x64_f8f6f4(A, B, C, 0, 0, 0, 0x7F7F7F7F, 0, 0x7F7F7F7F)
; template <bool FIRST>
; __device__ __forceinline__ void partialSM(f32x16& p0, f32x16& p1, f32x16& negm, float& dl, float& alpha) {
;     ...
;     for (int r = 0; r < 16; ++r) p0[r] = __builtin_amdgcn_exp2f(p0[r]);
; }
; __device__ __forceinline__ void finishSM(f32x16& p0, f32x16& p1, v8i& pa) {
; #pragma unroll
;     for (int r = 0; r < 16; ++r) p1[r] = __builtin_amdgcn_exp2f(p1[r]);
; #pragma unroll
;     for (int w = 0; w < 4; ++w) { pa[w] = (int)pk4_fp8(p0[4 * w], p0[4 * w + 1], p0[4 * w + 2], p0[4 * w + 3]); pa[4 + w] = (int)pk4_fp8(p1[4 * w], p1[4 * w + 1], p1[4 * w + 2], p1[4 * w + 3]); }
; }
; __device__ __forceinline__ v8i ld32(const LAS char* a0, const LAS char* a1) { const v4i x = *(const LAS v4i*)a0, y = *(const LAS v4i*)a1; return (v8i){x[0], x[1], x[2], x[3], y[0], y[1], y[2], y[3]}; }
; __device__ __forceinline__ void qkt(f32x16& p0, f32x16& p1, const LAS char* Ks, int ka0, int ka1, const v8i* qf, const f32x16& negm) {
; #pragma unroll
;     for (int st = 0; st < 3; ++st) {
;         const v8i k0 = ld32(Ks + ka0 + 64 * st, Ks + ka1 + 64 * st), k1 = ld32(Ks + ka0 + 64 * st + 32 * 192, Ks + ka1 + 64 * st + 32 * 192);
;         if (st == 0) { p0 = MFMA8QK(k0, qf[st], negm); p1 = MFMA8QK(k1, qf[st], negm); }
;         else { p0 = MFMA8QK(k0, qf[st], p0); p1 = MFMA8QK(k1, qf[st], p1); } }
; }
; __device__ __forceinline__ void pv_d0(f32x16* o, const LAS char* Vs, int va0, int va1, v8i pa) {
; #pragma unroll
;     for (int d0 = 0; d0 < 4; ++d0) { const v8i vf = ld32(Vs + va0 + 2048 * d0, Vs + va1 + 2048 * d0); o[d0] = MFMA8(pa, vf, o[d0]); }
;     const v8i ones = {0x38383838, 0x38383838, 0x38383838, 0x38383838, 0x38383838, 0x38383838, 0x38383838, 0x38383838};
;     o[4] = MFMA8(pa, ones, o[4]);
; __device__ __forceinline__ void attn_unit(const unsigned char* __restrict__ Qb, const unsigned char* __restrict__ Kh, const unsigned char* __restrict__ VTh, f16* __restrict__ Ob, int seq, LAS char* lds) {
;     ...
;         SBAR(); qkt(pB0, pB1, KSL(j), ka0, ka1, qf, negm);
;         finishSM(pA0, pA1, pa); SBAR();
;         pv_d0(o, VSL(j - 1), va0, va1, pa); partialSM<false>(pB0, pB1, negm, dlB, alB);
;         WBAR();
.LBB0_589:
	s_bitcmp1_b32 s15, 0
	s_cselect_b32 s0, 0x6000, 0
	s_add_i32 s0, s0, 0
	v_add_u32_e32 v0, s0, v244
	v_add_u32_e32 v210, s0, v245
	v_add_u32_e32 v211, 0xf000, v0
	v_add_u32_e32 v212, 0xf000, v210
	ds_read_b128 v[2:5], v0 offset:61504
	ds_read_b128 v[6:9], v210 offset:61504
	v_exp_f32_e32 v112, v112
	v_exp_f32_e32 v113, v113
	v_exp_f32_e32 v114, v114
	v_exp_f32_e32 v115, v115
	s_waitcnt lgkmcnt(4)
	v_mfma_scale_f32_32x32x64_f8f6f4 v[144:159], v[202:209], v[184:191], v[96:111], v234, v233 op_sel_hi:[0,0,0]
	ds_read_b128 v[202:205], v211 offset:6208
	ds_read_b128 v[206:209], v212 offset:6208
	v_exp_f32_e32 v116, v116
	v_exp_f32_e32 v117, v117
	v_exp_f32_e32 v118, v118
	v_exp_f32_e32 v119, v119
	v_exp_f32_e32 v120, v120
	v_exp_f32_e32 v121, v121
	s_waitcnt lgkmcnt(4)
	v_mfma_scale_f32_32x32x64_f8f6f4 v[128:143], v[194:201], v[184:191], v[96:111], v234, v233 op_sel_hi:[0,0,0]
	ds_read_b128 v[194:197], v0 offset:61568
	ds_read_b128 v[198:201], v210 offset:61568
	v_exp_f32_e32 v122, v122
	v_exp_f32_e32 v123, v123
	v_exp_f32_e32 v124, v124
	v_exp_f32_e32 v125, v125
	v_exp_f32_e32 v126, v126
	v_exp_f32_e32 v127, v127
	s_waitcnt lgkmcnt(4)
	v_mfma_scale_f32_32x32x64_f8f6f4 v[144:159], v[2:9], v[176:183], v[144:159], v234, v233 op_sel_hi:[0,0,0]
	ds_read_b128 v[2:5], v211 offset:6272
	ds_read_b128 v[6:9], v212 offset:6272
	v_pk_add_f32 v[80:81], v[80:81], v[112:113]
	v_pk_add_f32 v[82:83], v[82:83], v[114:115]
	v_pk_add_f32 v[80:81], v[80:81], v[116:117]
	v_pk_add_f32 v[82:83], v[82:83], v[118:119]
	v_pk_add_f32 v[80:81], v[80:81], v[120:121]
	v_pk_add_f32 v[82:83], v[82:83], v[122:123]
	s_waitcnt lgkmcnt(4)
	v_mfma_scale_f32_32x32x64_f8f6f4 v[128:143], v[202:209], v[176:183], v[128:143], v234, v233 op_sel_hi:[0,0,0]
	v_pk_add_f32 v[80:81], v[80:81], v[124:125]
	v_pk_add_f32 v[82:83], v[82:83], v[126:127]
	v_cvt_pk_fp8_f32 v117, v116, v117
	v_cvt_pk_fp8_f32 v116, v112, v113
	v_cvt_pk_fp8_f32 v117, v118, v119 op_sel:[0,0,1]
	v_cvt_pk_fp8_f32 v118, v120, v121
	s_waitcnt lgkmcnt(2)
	v_mfma_scale_f32_32x32x64_f8f6f4 v[144:159], v[194:201], v[168:175], v[144:159], v234, v233 op_sel_hi:[0,0,0]
	v_cvt_pk_fp8_f32 v119, v124, v125
	v_cvt_pk_fp8_f32 v116, v114, v115 op_sel:[0,0,1]
	v_cvt_pk_fp8_f32 v118, v122, v123 op_sel:[0,0,1]
	v_cvt_pk_fp8_f32 v119, v126, v127 op_sel:[0,0,1]
	v_cvt_pk_fp8_f32 v112, v228, v229
	v_cvt_pk_fp8_f32 v113, v226, v227
	s_waitcnt lgkmcnt(0)
	v_mfma_scale_f32_32x32x64_f8f6f4 v[128:143], v[2:9], v[168:175], v[128:143], v234, v233 op_sel_hi:[0,0,0]
	v_cvt_pk_fp8_f32 v114, v222, v223
	v_cvt_pk_fp8_f32 v115, v166, v167
	v_cvt_pk_fp8_f32 v112, v220, v221 op_sel:[0,0,1]
	v_cvt_pk_fp8_f32 v113, v224, v225 op_sel:[0,0,1]
	v_cvt_pk_fp8_f32 v114, v162, v163 op_sel:[0,0,1]
	v_cvt_pk_fp8_f32 v115, v164, v165 op_sel:[0,0,1]
	s_add_i32 s66, s21, -2
	s_ashr_i32 s38, s66, 1
	s_mul_hi_i32 s0, s38, 0x55555556
	s_lshr_b32 s1, s0, 31
	s_add_i32 s0, s0, s1
	s_mul_i32 s0, s0, 3
	s_sub_i32 s0, s38, s0
	s_lshl_b32 s0, s0, 14
	s_add_i32 s0, s0, 0
	v_add_u32_e32 v0, s0, v241
	v_add_u32_e32 v11, s0, v240
	ds_read_b128 v[208:211], v0
	ds_read_b128 v[212:215], v11
	ds_read_b128 v[200:203], v0 offset:2048
	ds_read_b128 v[204:207], v11 offset:2048
	ds_read_b128 v[192:195], v0 offset:4096
	ds_read_b128 v[196:199], v11 offset:4096
	ds_read_b128 v[2:5], v0 offset:6144
	ds_read_b128 v[6:9], v11 offset:6144
	v_mov_b32_e32 v125, 0x19000
	v_lshl_add_u32 v126, v216, 4, v125
	v_lshl_add_u32 v127, v216, 2, v125
	ds_read_b128 v[120:123], v126
	ds_read_b32 v124, v127 offset:8192
	v_max_f32_e32 v0, v145, v145
	v_max_f32_e32 v125, v144, v144
	v_max_f32_e32 v0, v125, v0
	v_max3_f32 v0, v0, v146, v147
	v_max3_f32 v0, v0, v148, v149
	v_max3_f32 v0, v0, v150, v151
	v_max3_f32 v0, v0, v152, v153
	v_max3_f32 v0, v0, v154, v155
	v_max3_f32 v0, v0, v156, v157
	v_max3_f32 v0, v0, v158, v159
	s_waitcnt lgkmcnt(8)
	v_mfma_scale_f32_32x32x64_f8f6f4 v[64:79], v[112:119], v[208:215], v[64:79], v234, v234 op_sel_hi:[0,0,0]
	v_exp_f32_e32 v14, v144
	v_exp_f32_e32 v15, v145
	v_exp_f32_e32 v10, v148
	v_exp_f32_e32 v11, v149
	v_max3_f32 v0, v0, v128, v129
	v_max3_f32 v0, v0, v130, v131
	v_max3_f32 v0, v0, v132, v133
	v_max3_f32 v0, v0, v134, v135
	v_pk_add_f32 v[80:81], v[80:81], v[14:15]
	v_pk_add_f32 v[82:83], v[82:83], v[10:11]
	s_waitcnt lgkmcnt(6)
	v_mfma_scale_f32_32x32x64_f8f6f4 v[48:63], v[112:119], v[200:207], v[48:63], v234, v234 op_sel_hi:[0,0,0]
	v_exp_f32_e32 v12, v150
	v_exp_f32_e32 v13, v151
	v_max3_f32 v0, v0, v136, v137
	v_max3_f32 v0, v0, v138, v139
	v_max3_f32 v0, v0, v140, v141
	v_max3_f32 v0, v0, v142, v143
	v_pk_add_f32 v[80:81], v[80:81], v[12:13]
	s_waitcnt lgkmcnt(4)
	v_mfma_scale_f32_32x32x64_f8f6f4 v[32:47], v[112:119], v[192:199], v[32:47], v234, v234 op_sel_hi:[0,0,0]
	v_exp_f32_e32 v192, v146
	v_exp_f32_e32 v193, v147
	v_mov_b32_e32 v125, v0
	s_nop 1
	v_permlane32_swap_b32_e32 v0, v125
	v_max_f32_e32 v125, v125, v125
	v_max_f32_e32 v0, v0, v0
	v_pk_add_f32 v[82:83], v[82:83], v[192:193]
	s_waitcnt lgkmcnt(2)
	v_mfma_scale_f32_32x32x64_f8f6f4 v[16:31], v[112:119], v[2:9], v[16:31], v234, v234 op_sel_hi:[0,0,0]
	v_exp_f32_e32 v6, v152
	v_exp_f32_e32 v7, v153
	v_exp_f32_e32 v8, v154
	v_exp_f32_e32 v9, v155
	v_exp_f32_e32 v2, v156
	v_exp_f32_e32 v3, v157
	v_exp_f32_e32 v4, v158
	v_exp_f32_e32 v5, v159
	v_pk_add_f32 v[80:81], v[80:81], v[6:7]
	v_pk_add_f32 v[82:83], v[82:83], v[8:9]
	v_pk_add_f32 v[80:81], v[80:81], v[2:3]
	v_pk_add_f32 v[82:83], v[82:83], v[4:5]
	s_waitcnt vmcnt(0) lgkmcnt(0)
	s_barrier
; #define WBAR() do { asm volatile("s_waitcnt vmcnt(0) lgkmcnt(0)" ::: "memory"); __builtin_amdgcn_s_barrier(); asm volatile("" ::: "memory"); } while (0)
; #define FIX(a, dlt, P0, P1) do { if (__any((dlt) > 0.f)) { if (hi == 0) al_l[r32] = (a); asm volatile("s_waitcnt lgkmcnt(0)" ::: "memory"); \
;     _Pragma("unroll") for (int d = 0; d < 5; ++d) _Pragma("unroll") for (int r = 0; r < 16; ++r) o[d][r] *= al_l[crow(r, hi)]; \
;     _Pragma("unroll") for (int r = 0; r < 16; ++r) { P0[r] *= (a); P1[r] -= (dlt); negm[r] -= (dlt); } } } while (0)
; __device__ __forceinline__ void attn_unit(const unsigned char* __restrict__ Qb, const unsigned char* __restrict__ Kh, const unsigned char* __restrict__ VTh, f16* __restrict__ Ob, int seq, LAS char* lds) {
;     ...
;         WBAR();
;         { const int J = (j - 1) >> 1; if (J + 2 < NS) ISSUE(J + 2); }
;         FIX(alB, dlB, pB0, pB1);
	v_max_f32_e32 v0, v0, v125
	s_add_i32 s42, s38, 2
	v_cmp_ge_f32_e64 s[0:1], s67, v0
	s_cmp_ge_i32 s42, s14
	s_cbranch_scc1 .Lattn_noissue
	s_bitcmp1_b32 s21, 1
	s_cselect_b32 s44, 0x6000, 0
	v_add_u32_e32 v126, s44, v244
	v_add_u32_e32 v127, s44, v245
	ds_read_b128 v[208:211], v126 offset:49152
	ds_read_b128 v[212:215], v127 offset:49152
	s_ashr_i32 s43, s42, 31
	s_mul_i32 s38, s42, 0x18000
	s_mul_hi_i32 s39, s42, 0x18000
	s_add_u32 s38, s24, s38
	s_addc_u32 s39, s25, s39
	s_lshl_b64 s[40:41], s[42:43], 14
	s_add_u32 s40, s52, s40
	s_addc_u32 s41, s53, s41
	s_mul_hi_i32 s43, s42, 0x55555556
	s_lshr_b32 s67, s43, 31
	s_add_i32 s43, s43, s67
	s_mul_i32 s43, s43, 3
	s_sub_i32 s42, s42, s43
	s_lshl_b32 s67, s42, 14
	s_bitcmp1_b32 s66, 1
	s_mov_b32 s42, 0xa000
	s_cselect_b32 s66, 0x10000, s42
	s_add_i32 s42, s67, s28
	s_add_i32 s43, s29, s66
	s_and_b64 vcc, s[54:55], exec
	s_cselect_b32 s42, s42, s43
	s_mov_b32 m0, s42
	s_and_b64 vcc, exec, s[56:57]
	s_cselect_b32 s44, s38, s40
	s_cselect_b32 s45, s39, s41
	global_load_lds_dwordx4 v120, s[44:45]
	s_add_i32 s42, s67, s35
	s_add_i32 s43, s2, s66
	s_and_b64 vcc, s[58:59], exec
	s_cselect_b32 s42, s42, s43
	s_mov_b32 m0, s42
	s_and_b64 vcc, exec, s[4:5]
	s_cselect_b32 s44, s40, s38
	s_cselect_b32 s45, s41, s39
	global_load_lds_dwordx4 v121, s[44:45]
	s_add_i32 s42, s67, s26
	s_add_i32 s43, s27, s66
	s_and_b64 vcc, s[60:61], exec
	s_cselect_b32 s42, s42, s43
	s_mov_b32 m0, s42
	s_and_b64 vcc, exec, s[6:7]
	s_cselect_b32 s44, s40, s38
	s_cselect_b32 s45, s41, s39
	global_load_lds_dwordx4 v122, s[44:45]
	s_add_i32 s42, s67, s31
	s_add_i32 s43, s49, s66
	s_and_b64 vcc, s[62:63], exec
	s_cselect_b32 s42, s42, s43
	s_mov_b32 m0, s42
	s_and_b64 vcc, exec, s[8:9]
	s_cselect_b32 s44, s40, s38
	s_cselect_b32 s45, s41, s39
	global_load_lds_dwordx4 v123, s[44:45]
	s_add_i32 s42, s67, s18
	s_add_i32 s43, s33, s66
	s_and_b64 vcc, s[64:65], exec
	s_cselect_b32 s42, s42, s43
	s_mov_b32 m0, s42
	s_and_b64 vcc, exec, s[10:11]
	s_cselect_b32 s44, s40, s38
	s_cselect_b32 s45, s41, s39
	global_load_lds_dwordx4 v124, s[44:45]
	s_mov_b32 s67, 0x41000000
	ds_read_b128 v[120:123], v126 offset:55296
	ds_read_b128 v[124:127], v127 offset:55296
	v_add_f32_e32 v0, -4.0, v0
	s_cmp_lg_u64 s[0:1], exec
	v_max_f32_e32 v0, 0, v0
	s_cselect_b64 vcc, -1, 0
	v_cndmask_b32_e32 v0, 0, v0, vcc
	v_cmp_lt_f32_e32 vcc, 0, v0
	s_cbranch_vccz .LBB0_615
	s_branch .Lattn_fix1

; #define SBAR() __builtin_amdgcn_sched_barrier(0)
; #define FIX(a, dlt, P0, P1) do { if (__any((dlt) > 0.f)) { if (hi == 0) al_l[r32] = (a); asm volatile("s_waitcnt lgkmcnt(0)" ::: "memory"); \
;     _Pragma("unroll") for (int d = 0; d < 5; ++d) _Pragma("unroll") for (int r = 0; r < 16; ++r) o[d][r] *= al_l[crow(r, hi)]; \
;     _Pragma("unroll") for (int r = 0; r < 16; ++r) { P0[r] *= (a); P1[r] -= (dlt); negm[r] -= (dlt); } } } while (0)
; __device__ __forceinline__ void attn_unit(const unsigned char* __restrict__ Qb, const unsigned char* __restrict__ Kh, const unsigned char* __restrict__ VTh, f16* __restrict__ Ob, int seq, LAS char* lds) {
;     ...
;         FIX(alB, dlB, pB0, pB1);
;         SBAR(); qkt(pA0, pA1, KSL(j + 1), ka0, ka1, qf, negm);
;         finishSM(pB0, pB1, pa); SBAR();
;         pv_d0(o, VSL(j), va0, va1, pa); partialSM<false>(pA0, pA1, negm, dlA, alA);
.Lattn_fix1:
	v_exp_f32_e64 v112, -v0
	s_and_saveexec_b64 s[0:1], s[12:13]
	ds_write_b32 v243, v112 offset:128
	s_or_b64 exec, exec, s[0:1]
	s_waitcnt lgkmcnt(0)
	v_add_u32_e32 v113, s20, v242
	ds_read_b128 v[114:117], v113 offset:224
	ds_read_b128 v[118:121], v113 offset:192
	ds_read_b128 v[122:125], v113 offset:160
	ds_read_b128 v[144:147], v113 offset:128
	v_pk_add_f32 v[128:129], v[128:129], v[0:1] op_sel_hi:[1,0] neg_lo:[0,1] neg_hi:[0,1]
	s_waitcnt lgkmcnt(0)
	v_pk_mul_f32 v[76:77], v[76:77], v[114:115]
	v_pk_mul_f32 v[72:73], v[72:73], v[118:119]
	v_pk_mul_f32 v[68:69], v[68:69], v[122:123]
	v_pk_mul_f32 v[78:79], v[78:79], v[116:117]
	v_pk_mul_f32 v[74:75], v[74:75], v[120:121]
	v_pk_mul_f32 v[70:71], v[70:71], v[124:125]
	v_pk_mul_f32 v[66:67], v[66:67], v[146:147]
	v_pk_mul_f32 v[64:65], v[64:65], v[144:145]
	v_pk_mul_f32 v[60:61], v[60:61], v[114:115]
	v_pk_mul_f32 v[56:57], v[56:57], v[118:119]
	v_pk_mul_f32 v[52:53], v[52:53], v[122:123]
	v_pk_mul_f32 v[62:63], v[62:63], v[116:117]
	v_pk_mul_f32 v[58:59], v[58:59], v[120:121]
	v_pk_mul_f32 v[54:55], v[54:55], v[124:125]
	v_pk_mul_f32 v[50:51], v[50:51], v[146:147]
	v_pk_mul_f32 v[48:49], v[48:49], v[144:145]
	v_pk_mul_f32 v[44:45], v[44:45], v[114:115]
	v_pk_mul_f32 v[40:41], v[40:41], v[118:119]
	v_pk_mul_f32 v[36:37], v[36:37], v[122:123]
	v_pk_mul_f32 v[46:47], v[46:47], v[116:117]
	v_pk_mul_f32 v[42:43], v[42:43], v[120:121]
	v_pk_mul_f32 v[38:39], v[38:39], v[124:125]
	v_pk_mul_f32 v[34:35], v[34:35], v[146:147]
	v_pk_mul_f32 v[32:33], v[32:33], v[144:145]
	v_pk_mul_f32 v[28:29], v[28:29], v[114:115]
	v_pk_mul_f32 v[24:25], v[24:25], v[118:119]
	v_pk_mul_f32 v[20:21], v[20:21], v[122:123]
	v_pk_mul_f32 v[30:31], v[30:31], v[116:117]
	v_pk_mul_f32 v[26:27], v[26:27], v[120:121]
	v_pk_mul_f32 v[22:23], v[22:23], v[124:125]
	v_pk_mul_f32 v[18:19], v[18:19], v[146:147]
	v_pk_mul_f32 v[16:17], v[16:17], v[144:145]
	v_pk_mul_f32 v[80:81], v[80:81], v[112:113] op_sel_hi:[1,0]
	v_pk_mul_f32 v[82:83], v[82:83], v[112:113] op_sel_hi:[1,0]
	v_pk_add_f32 v[130:131], v[130:131], v[0:1] op_sel_hi:[1,0] neg_lo:[0,1] neg_hi:[0,1]
	v_pk_add_f32 v[132:133], v[132:133], v[0:1] op_sel_hi:[1,0] neg_lo:[0,1] neg_hi:[0,1]
	v_pk_add_f32 v[134:135], v[134:135], v[0:1] op_sel_hi:[1,0] neg_lo:[0,1] neg_hi:[0,1]
	v_pk_add_f32 v[136:137], v[136:137], v[0:1] op_sel_hi:[1,0] neg_lo:[0,1] neg_hi:[0,1]
	v_pk_add_f32 v[138:139], v[138:139], v[0:1] op_sel_hi:[1,0] neg_lo:[0,1] neg_hi:[0,1]
	v_pk_add_f32 v[140:141], v[140:141], v[0:1] op_sel_hi:[1,0] neg_lo:[0,1] neg_hi:[0,1]
	v_pk_mul_f32 v[4:5], v[4:5], v[112:113] op_sel_hi:[1,0]
	v_pk_mul_f32 v[2:3], v[2:3], v[112:113] op_sel_hi:[1,0]
	v_pk_mul_f32 v[8:9], v[8:9], v[112:113] op_sel_hi:[1,0]
	v_pk_mul_f32 v[6:7], v[6:7], v[112:113] op_sel_hi:[1,0]
	v_pk_mul_f32 v[12:13], v[12:13], v[112:113] op_sel_hi:[1,0]
	v_pk_mul_f32 v[10:11], v[10:11], v[112:113] op_sel_hi:[1,0]
	v_pk_mul_f32 v[192:193], v[192:193], v[112:113] op_sel_hi:[1,0]
	v_pk_mul_f32 v[14:15], v[14:15], v[112:113] op_sel_hi:[1,0]
	v_pk_add_f32 v[142:143], v[142:143], v[0:1] op_sel_hi:[1,0] neg_lo:[0,1] neg_hi:[0,1]
	v_sub_f32_e32 v111, v111, v0
	v_sub_f32_e32 v110, v110, v0
	v_sub_f32_e32 v109, v109, v0
	v_sub_f32_e32 v108, v108, v0
	v_sub_f32_e32 v107, v107, v0
	v_sub_f32_e32 v106, v106, v0
	v_sub_f32_e32 v105, v105, v0
	v_sub_f32_e32 v104, v104, v0
	v_sub_f32_e32 v103, v103, v0
	v_sub_f32_e32 v102, v102, v0
	v_sub_f32_e32 v101, v101, v0
	v_sub_f32_e32 v100, v100, v0
	v_sub_f32_e32 v99, v99, v0
	v_sub_f32_e32 v98, v98, v0
	v_sub_f32_e32 v97, v97, v0
	v_sub_f32_e32 v96, v96, v0
	s_bitcmp1_b32 s21, 1
	s_cselect_b32 s0, 0x6000, 0
	v_add_u32_e32 v126, s0, v244
	v_add_u32_e32 v127, s0, v245
	ds_read_b128 v[120:123], v126 offset:55296
	ds_read_b128 v[124:127], v127 offset:55296
.LBB0_615:
	s_mul_hi_u32 s0, s15, 0xaaaaaaab
	s_lshr_b32 s0, s0, 1
	s_mul_i32 s0, s0, 0xffff4000
	s_bfe_i32 s1, s21, 0x10001
	s_and_b32 s1, s1, 0x6000
	s_add_i32 s1, s1, 0
	v_add_u32_e32 v0, s1, v244
	v_add_u32_e32 v161, s1, v245
	ds_read_b128 v[194:197], v0 offset:55360
	ds_read_b128 v[198:201], v161 offset:55360
	v_exp_f32_e32 v129, v129
	v_exp_f32_e32 v133, v133
	s_waitcnt lgkmcnt(4)
	v_mfma_scale_f32_32x32x64_f8f6f4 v[144:159], v[208:215], v[184:191], v[96:111], v234, v233 op_sel_hi:[0,0,0]
	ds_read_b128 v[202:205], v0 offset:49216
	ds_read_b128 v[206:209], v161 offset:49216
	v_exp_f32_e32 v130, v130
	v_exp_f32_e32 v131, v131
	v_exp_f32_e32 v134, v134
	v_exp_f32_e32 v135, v135
	v_exp_f32_e32 v136, v136
	v_exp_f32_e32 v137, v137
	v_exp_f32_e32 v140, v140
	v_exp_f32_e32 v141, v141
	v_exp_f32_e32 v138, v138
	v_exp_f32_e32 v139, v139
	v_exp_f32_e32 v142, v142
	v_exp_f32_e32 v143, v143
	v_exp_f32_e32 v128, v128
	v_exp_f32_e32 v132, v132
	s_waitcnt lgkmcnt(4)
	v_mfma_scale_f32_32x32x64_f8f6f4 v[112:127], v[120:127], v[184:191], v[96:111], v234, v233 op_sel_hi:[0,0,0]
	s_waitcnt lgkmcnt(2)
	v_mfma_scale_f32_32x32x64_f8f6f4 v[112:127], v[194:201], v[176:183], v[112:127], v234, v233 op_sel_hi:[0,0,0]
	s_waitcnt lgkmcnt(0)
	v_mfma_scale_f32_32x32x64_f8f6f4 v[144:159], v[202:209], v[176:183], v[144:159], v234, v233 op_sel_hi:[0,0,0]
	ds_read_b128 v[194:197], v0 offset:55424
	ds_read_b128 v[198:201], v161 offset:55424
	ds_read_b128 v[202:205], v0 offset:49280
	ds_read_b128 v[206:209], v161 offset:49280
	v_pk_add_f32 v[80:81], v[80:81], v[128:129]
	v_pk_add_f32 v[82:83], v[82:83], v[130:131]
	v_pk_add_f32 v[80:81], v[80:81], v[132:133]
	v_pk_add_f32 v[82:83], v[82:83], v[134:135]
	v_pk_add_f32 v[80:81], v[80:81], v[136:137]
	v_pk_add_f32 v[82:83], v[82:83], v[138:139]
	v_pk_add_f32 v[80:81], v[80:81], v[140:141]
	v_pk_add_f32 v[82:83], v[82:83], v[142:143]
	v_cvt_pk_fp8_f32 v133, v132, v133
	v_cvt_pk_fp8_f32 v132, v128, v129
	v_cvt_pk_fp8_f32 v133, v134, v135 op_sel:[0,0,1]
	v_cvt_pk_fp8_f32 v134, v136, v137
	v_cvt_pk_fp8_f32 v135, v140, v141
	s_waitcnt lgkmcnt(0)
; #define LAS __attribute__((address_space(3)))
; #define MFMA8(A, B, C) __builtin_amdgcn_mfma_scale_f32_32x32x64_f8f6f4(A, B, C, 0, 0, 0, 0x7F7F7F7F, 0, 0x7F7F7F7F)
; __device__ __forceinline__ v8i ld32(const LAS char* a0, const LAS char* a1) { const v4i x = *(const LAS v4i*)a0, y = *(const LAS v4i*)a1; return (v8i){x[0], x[1], x[2], x[3], y[0], y[1], y[2], y[3]}; }
; #define MFMA8QK(A, B, C) __builtin_amdgcn_mfma_scale_f32_32x32x64_f8f6f4(A, B, C, 0, 0, 0, 0x7F7F7F7F, 0, 0x7C7C7C7C)
; #define FIX(a, dlt, P0, P1) do { if (__any((dlt) > 0.f)) { if (hi == 0) al_l[r32] = (a); asm volatile("s_waitcnt lgkmcnt(0)" ::: "memory"); \
;     _Pragma("unroll") for (int d = 0; d < 5; ++d) _Pragma("unroll") for (int r = 0; r < 16; ++r) o[d][r] *= al_l[crow(r, hi)]; \
;     _Pragma("unroll") for (int r = 0; r < 16; ++r) { P0[r] *= (a); P1[r] -= (dlt); negm[r] -= (dlt); } } } while (0)
; __device__ __forceinline__ void qkt(f32x16& p0, f32x16& p1, const LAS char* Ks, int ka0, int ka1, const v8i* qf, const f32x16& negm) {
; #pragma unroll
;     for (int st = 0; st < 3; ++st) {
;         const v8i k0 = ld32(Ks + ka0 + 64 * st, Ks + ka1 + 64 * st), k1 = ld32(Ks + ka0 + 64 * st + 32 * 192, Ks + ka1 + 64 * st + 32 * 192);
;         if (st == 0) { p0 = MFMA8QK(k0, qf[st], negm); p1 = MFMA8QK(k1, qf[st], negm); }
;         else { p0 = MFMA8QK(k0, qf[st], p0); p1 = MFMA8QK(k1, qf[st], p1); } }
; }
; __device__ __forceinline__ void pv_d0(f32x16* o, const LAS char* Vs, int va0, int va1, v8i pa) {
; #pragma unroll
;     for (int d0 = 0; d0 < 4; ++d0) { const v8i vf = ld32(Vs + va0 + 2048 * d0, Vs + va1 + 2048 * d0); o[d0] = MFMA8(pa, vf, o[d0]); }
;     const v8i ones = {0x38383838, 0x38383838, 0x38383838, 0x38383838, 0x38383838, 0x38383838, 0x38383838, 0x38383838};
;     o[4] = MFMA8(pa, ones, o[4]);
; __device__ __forceinline__ void attn_unit(const unsigned char* __restrict__ Qb, const unsigned char* __restrict__ Kh, const unsigned char* __restrict__ VTh, f16* __restrict__ Ob, int seq, LAS char* lds) {
;     ...
;         pv_d0(o, VSL(j), va0, va1, pa); partialSM<false>(pA0, pA1, negm, dlA, alA);
;         FIX(alA, dlA, pA0, pA1);
	v_mfma_scale_f32_32x32x64_f8f6f4 v[112:127], v[194:201], v[168:175], v[112:127], v234, v233 op_sel_hi:[0,0,0]
	v_cvt_pk_fp8_f32 v132, v130, v131 op_sel:[0,0,1]
	v_cvt_pk_fp8_f32 v134, v138, v139 op_sel:[0,0,1]
	v_cvt_pk_fp8_f32 v135, v142, v143 op_sel:[0,0,1]
	v_cvt_pk_fp8_f32 v128, v14, v15
	v_cvt_pk_fp8_f32 v129, v10, v11
	v_cvt_pk_fp8_f32 v130, v6, v7
	v_cvt_pk_fp8_f32 v131, v2, v3
	v_cvt_pk_fp8_f32 v128, v192, v193 op_sel:[0,0,1]
	v_cvt_pk_fp8_f32 v129, v12, v13 op_sel:[0,0,1]
	v_cvt_pk_fp8_f32 v130, v8, v9 op_sel:[0,0,1]
	v_cvt_pk_fp8_f32 v131, v4, v5 op_sel:[0,0,1]
	v_or_b32_e32 v10, s0, v218
	v_or_b32_e32 v11, s0, v250
	v_add_u32_e32 v10, v247, v10
	v_add_u32_e32 v11, v247, v11
	ds_read_b128 v[2:5], v10
	ds_read_b128 v[6:9], v11
	v_mfma_scale_f32_32x32x64_f8f6f4 v[144:159], v[202:209], v[168:175], v[144:159], v234, v233 op_sel_hi:[0,0,0]
	ds_read_b128 v[194:197], v10 offset:2048
	ds_read_b128 v[198:201], v11 offset:2048
	s_waitcnt lgkmcnt(2)
	v_mfma_scale_f32_32x32x64_f8f6f4 v[64:79], v[128:135], v[2:9], v[64:79], v234, v234 op_sel_hi:[0,0,0]
	ds_read_b128 v[2:5], v10 offset:4096
	ds_read_b128 v[6:9], v11 offset:4096
	s_waitcnt lgkmcnt(2)
	v_mfma_scale_f32_32x32x64_f8f6f4 v[48:63], v[128:135], v[194:201], v[48:63], v234, v234 op_sel_hi:[0,0,0]
	ds_read_b128 v[194:197], v10 offset:6144
	ds_read_b128 v[198:201], v11 offset:6144
	s_nop 7
	s_nop 1
	v_exp_f32_e32 v228, v144
	v_exp_f32_e32 v229, v145
	v_exp_f32_e32 v220, v146
	v_exp_f32_e32 v221, v147
	v_exp_f32_e32 v226, v148
	v_exp_f32_e32 v227, v149
	v_exp_f32_e32 v224, v150
	v_exp_f32_e32 v225, v151
	v_exp_f32_e32 v222, v152
	v_exp_f32_e32 v223, v153
	v_max_f32_e32 v0, v145, v145
	v_pk_add_f32 v[80:81], v[80:81], v[228:229]
	v_pk_add_f32 v[82:83], v[82:83], v[220:221]
	v_pk_add_f32 v[80:81], v[80:81], v[226:227]
	v_pk_add_f32 v[82:83], v[82:83], v[224:225]
	v_pk_add_f32 v[80:81], v[80:81], v[222:223]
	s_waitcnt lgkmcnt(2)
	v_mfma_scale_f32_32x32x64_f8f6f4 v[32:47], v[128:135], v[2:9], v[32:47], v234, v234 op_sel_hi:[0,0,0]
	v_max_f32_e32 v2, v144, v144
	v_max_f32_e32 v0, v2, v0
	v_max3_f32 v0, v0, v146, v147
	v_max3_f32 v0, v0, v148, v149
	v_max3_f32 v0, v0, v150, v151
	v_max3_f32 v0, v0, v152, v153
	v_max3_f32 v0, v0, v154, v155
	v_max3_f32 v0, v0, v156, v157
	v_max3_f32 v0, v0, v158, v159
	s_waitcnt lgkmcnt(0)
	v_mfma_scale_f32_32x32x64_f8f6f4 v[16:31], v[128:135], v[194:201], v[16:31], v234, v234 op_sel_hi:[0,0,0]
	s_bitcmp0_b32 s15, 0
	s_cselect_b32 s1, 0x6000, 0
	v_add_u32_e32 v12, s1, v244
	v_add_u32_e32 v13, s1, v245
	v_add_u32_e32 v14, 0xf000, v12
	v_add_u32_e32 v15, 0xf000, v13
	ds_read_b128 v[202:205], v12 offset:61440
	ds_read_b128 v[206:209], v13 offset:61440
	ds_read_b128 v[194:197], v14 offset:6144
	ds_read_b128 v[198:201], v15 offset:6144
	v_max3_f32 v0, v0, v112, v113
	v_max3_f32 v0, v0, v114, v115
	v_max3_f32 v0, v0, v116, v117
	v_max3_f32 v0, v0, v118, v119
	v_max3_f32 v0, v0, v120, v121
	v_max3_f32 v0, v0, v122, v123
	v_max3_f32 v0, v0, v124, v125
	v_max3_f32 v0, v0, v126, v127
	v_mov_b32_e32 v2, v0
	s_nop 1
	v_permlane32_swap_b32_e32 v0, v2
	v_max_f32_e32 v2, v2, v2
	v_max_f32_e32 v0, v0, v0
	v_max_f32_e32 v0, v0, v2
	v_cmp_ge_f32_e32 vcc, s67, v0
	v_add_f32_e32 v0, -4.0, v0
	s_cmp_lg_u64 vcc, exec
	v_exp_f32_e32 v162, v154
	v_exp_f32_e32 v163, v155
	v_exp_f32_e32 v166, v156
	v_exp_f32_e32 v167, v157
	v_exp_f32_e32 v164, v158
	v_exp_f32_e32 v165, v159
	v_max_f32_e32 v0, 0, v0
	v_pk_add_f32 v[80:81], v[80:81], v[162:163]
	v_pk_add_f32 v[82:83], v[82:83], v[166:167]
	v_pk_add_f32 v[80:81], v[80:81], v[164:165]
	s_cselect_b64 vcc, -1, 0
	v_cndmask_b32_e32 v2, 0, v0, vcc
	v_cmp_lt_f32_e32 vcc, 0, v2
	s_cbranch_vccz .LBB0_588
	v_exp_f32_e64 v0, -v2
	s_and_saveexec_b64 s[0:1], s[12:13]
	s_cbranch_execz .LBB0_587
	ds_write_b32 v243, v0 offset:128
	s_branch .LBB0_587
; #define SBAR() __builtin_amdgcn_sched_barrier(0)
; #define FIX(a, dlt, P0, P1) do { if (__any((dlt) > 0.f)) { if (hi == 0) al_l[r32] = (a); asm volatile("s_waitcnt lgkmcnt(0)" ::: "memory"); \
;     _Pragma("unroll") for (int d = 0; d < 5; ++d) _Pragma("unroll") for (int r = 0; r < 16; ++r) o[d][r] *= al_l[crow(r, hi)]; \
;     _Pragma("unroll") for (int r = 0; r < 16; ++r) { P0[r] *= (a); P1[r] -= (dlt); negm[r] -= (dlt); } } } while (0)
; __device__ __forceinline__ void attn_unit(const unsigned char* __restrict__ Qb, const unsigned char* __restrict__ Kh, const unsigned char* __restrict__ VTh, f16* __restrict__ Ob, int seq, LAS char* lds) {
;     ...
;     SBAR(); qkt(pB0, pB1, KSL(NT - 1), ka0, ka1, qf, negm);
;     finishSM(pA0, pA1, pa); SBAR();
;     pv_d0(o, VSL(NT - 2), va0, va1, pa); partialSM<false>(pB0, pB1, negm, dlB, alB);
;     FIX(alB, dlB, pB0, pB1);
.LBB0_618:
	v_readlane_b32 s0, v253, 7
	v_exp_f32_e32 v13, v116
	v_exp_f32_e32 v14, v117
	v_add_u32_e32 v0, s0, v244
	v_add_u32_e32 v10, s0, v245
	ds_read_b128 v[2:5], v0
	ds_read_b128 v[6:9], v10
	v_exp_f32_e32 v116, v124
	s_waitcnt lgkmcnt(0)
	v_mfma_scale_f32_32x32x64_f8f6f4 v[128:143], v[2:9], v[184:191], v[96:111], v234, v233 op_sel_hi:[0,0,0]
	ds_read_b128 v[2:5], v0 offset:6144
	ds_read_b128 v[6:9], v10 offset:6144
	v_exp_f32_e32 v117, v125
	v_exp_f32_e32 v11, v114
	v_exp_f32_e32 v12, v115
	v_exp_f32_e32 v15, v118
	v_exp_f32_e32 v114, v122
	v_exp_f32_e32 v115, v123
	v_exp_f32_e32 v118, v126
	s_waitcnt lgkmcnt(0)
	v_mfma_scale_f32_32x32x64_f8f6f4 v[96:111], v[2:9], v[184:191], v[96:111], v234, v233 op_sel_hi:[0,0,0]
	ds_read_b128 v[2:5], v0 offset:64
	ds_read_b128 v[6:9], v10 offset:64
	s_waitcnt lgkmcnt(0)
	v_mfma_scale_f32_32x32x64_f8f6f4 v[128:143], v[2:9], v[176:183], v[128:143], v234, v233 op_sel_hi:[0,0,0]
	ds_read_b128 v[2:5], v0 offset:6208
	ds_read_b128 v[6:9], v10 offset:6208
	ds_read_b128 v[144:147], v0 offset:6272
	ds_read_b128 v[148:151], v10 offset:6272
	ds_read_b128 v[152:155], v0 offset:128
	ds_read_b128 v[156:159], v10 offset:128
	v_exp_f32_e32 v10, v113
	v_exp_f32_e32 v113, v120
	v_exp_f32_e32 v0, v112
	v_exp_f32_e32 v112, v119
	v_exp_f32_e32 v119, v127
	s_waitcnt lgkmcnt(0)
	v_mfma_scale_f32_32x32x64_f8f6f4 v[96:111], v[2:9], v[176:183], v[96:111], v234, v233 op_sel_hi:[0,0,0]
	v_exp_f32_e32 v5, v121
	v_mov_b32_e32 v8, v1
	v_mov_b32_e32 v2, v1
	v_mov_b32_e32 v6, v1
	v_mov_b32_e32 v3, v1
	v_mov_b32_e32 v7, v1
	v_mov_b32_e32 v4, v1
	v_add_f32_e32 v80, v80, v13
	v_add_f32_e32 v82, v82, v14
	v_add_f32_e32 v80, v80, v116
	v_add_f32_e32 v82, v82, v117
	v_add_f32_e32 v80, v80, v11
	v_add_f32_e32 v82, v82, v12
	v_add_f32_e32 v80, v80, v15
	v_add_f32_e32 v82, v82, v114
	v_add_f32_e32 v80, v80, v115
	v_add_f32_e32 v82, v82, v118
	v_add_f32_e32 v80, v80, v10
	v_add_f32_e32 v82, v82, v113
	v_add_f32_e32 v80, v80, v0
	v_add_f32_e32 v82, v82, v112
	v_add_f32_e32 v80, v80, v119
	v_add_f32_e32 v82, v82, v5
	v_cvt_pk_fp8_f32 v8, v113, v5
	v_mov_b32_e32 v5, v1
	v_mov_b32_e32 v9, v1
	v_cvt_pk_fp8_f32 v2, v228, v229
	v_cvt_pk_fp8_f32 v6, v0, v10
	v_cvt_pk_fp8_f32 v3, v226, v227
	v_cvt_pk_fp8_f32 v7, v13, v14
	v_cvt_pk_fp8_f32 v4, v222, v223
	v_mfma_scale_f32_32x32x64_f8f6f4 v[96:111], v[144:151], v[168:175], v[96:111], v234, v233 op_sel_hi:[0,0,0]
	v_cvt_pk_fp8_f32 v5, v166, v167
	v_cvt_pk_fp8_f32 v9, v116, v117
	v_cvt_pk_fp8_f32 v2, v220, v221 op_sel:[0,0,1]
	v_cvt_pk_fp8_f32 v6, v11, v12 op_sel:[0,0,1]
	v_cvt_pk_fp8_f32 v3, v224, v225 op_sel:[0,0,1]
	v_cvt_pk_fp8_f32 v7, v15, v112 op_sel:[0,0,1]
	v_cvt_pk_fp8_f32 v4, v162, v163 op_sel:[0,0,1]
	v_cvt_pk_fp8_f32 v8, v114, v115 op_sel:[0,0,1]
	v_cvt_pk_fp8_f32 v5, v164, v165 op_sel:[0,0,1]
	v_cvt_pk_fp8_f32 v9, v118, v119 op_sel:[0,0,1]
	v_mfma_scale_f32_32x32x64_f8f6f4 v[128:143], v[152:159], v[168:175], v[128:143], v234, v233 op_sel_hi:[0,0,0]
	s_add_i32 s0, s47, -2
	s_lshr_b32 s0, s0, 1
	s_mul_hi_u32 s1, s0, 0x55555556
	s_mul_i32 s1, s1, 3
	s_sub_i32 s0, s0, s1
	s_lshl_b32 s0, s0, 14
	s_add_i32 s0, s0, 0
	v_add_u32_e32 v0, s0, v241
	v_add_u32_e32 v10, s0, v240
	ds_read_b128 v[112:115], v0
	ds_read_b128 v[116:119], v10
	v_mov_b32_e32 v161, v160
	v_mov_b32_e32 v162, v160
	v_mov_b32_e32 v163, v160
	s_waitcnt lgkmcnt(0)
	v_mfma_scale_f32_32x32x64_f8f6f4 v[64:79], v[2:9], v[112:119], v[64:79], v234, v234 op_sel_hi:[0,0,0]
	ds_read_b128 v[112:115], v0 offset:2048
	ds_read_b128 v[116:119], v10 offset:2048
	v_mov_b32_e32 v164, v160
	v_mov_b32_e32 v165, v160
	v_mov_b32_e32 v166, v160
	v_mov_b32_e32 v167, v160
	v_exp_f32_e32 v14, v128
	v_exp_f32_e32 v15, v129
	v_exp_f32_e32 v12, v134
	v_exp_f32_e32 v13, v135
	v_exp_f32_e32 v11, v137
	s_waitcnt lgkmcnt(0)
	v_mfma_scale_f32_32x32x64_f8f6f4 v[48:63], v[2:9], v[112:119], v[48:63], v234, v234 op_sel_hi:[0,0,0]
	ds_read_b128 v[112:115], v0 offset:4096
	ds_read_b128 v[116:119], v10 offset:4096
	s_waitcnt lgkmcnt(0)
	v_mfma_scale_f32_32x32x64_f8f6f4 v[32:47], v[2:9], v[112:119], v[32:47], v234, v234 op_sel_hi:[0,0,0]
	ds_read_b128 v[112:115], v0 offset:6144
	ds_read_b128 v[116:119], v10 offset:6144
	v_max_f32_e32 v0, v129, v129
	v_exp_f32_e32 v10, v136
	s_waitcnt lgkmcnt(0)
	v_mfma_scale_f32_32x32x64_f8f6f4 v[16:31], v[2:9], v[112:119], v[16:31], v234, v234 op_sel_hi:[0,0,0]
	v_exp_f32_e32 v112, v132
	v_exp_f32_e32 v113, v133
	v_max_f32_e32 v2, v128, v128
	v_max_f32_e32 v0, v2, v0
	v_max3_f32 v0, v0, v130, v131
	v_max3_f32 v0, v0, v132, v133
	v_max3_f32 v0, v0, v134, v135
	v_max3_f32 v0, v0, v136, v137
	v_max3_f32 v0, v0, v138, v139
	v_max3_f32 v0, v0, v140, v141
	v_max3_f32 v0, v0, v142, v143
	v_max3_f32 v0, v0, v96, v97
	v_max3_f32 v0, v0, v98, v99
	v_max3_f32 v0, v0, v100, v101
	v_max3_f32 v0, v0, v102, v103
	v_max3_f32 v0, v0, v104, v105
	v_max3_f32 v0, v0, v106, v107
	v_max3_f32 v0, v0, v108, v109
	v_max3_f32 v0, v0, v110, v111
	v_mov_b32_e32 v2, v0
	s_nop 1
	v_permlane32_swap_b32_e32 v0, v2
	v_max_f32_e32 v2, v2, v2
	v_max_f32_e32 v0, v0, v0
	v_max_f32_e32 v0, v0, v2
	v_cmp_ge_f32_e32 vcc, s67, v0
	v_add_f32_e32 v0, -4.0, v0
	s_cmp_lg_u64 vcc, exec
	v_exp_f32_e32 v8, v130
	v_exp_f32_e32 v9, v131
	v_exp_f32_e32 v2, v138
	v_exp_f32_e32 v3, v139
	v_exp_f32_e32 v6, v140
	v_exp_f32_e32 v7, v141
	v_exp_f32_e32 v4, v142
	v_exp_f32_e32 v5, v143
	v_max_f32_e32 v0, 0, v0
	v_add_f32_e32 v80, v80, v14
	v_add_f32_e32 v82, v82, v15
	v_add_f32_e32 v80, v80, v12
	v_add_f32_e32 v82, v82, v13
	v_add_f32_e32 v80, v80, v11
	v_add_f32_e32 v82, v82, v10
	v_add_f32_e32 v80, v80, v112
	v_add_f32_e32 v82, v82, v113
	v_add_f32_e32 v80, v80, v8
	v_add_f32_e32 v82, v82, v9
	v_add_f32_e32 v80, v80, v2
	v_add_f32_e32 v82, v82, v3
	v_add_f32_e32 v80, v80, v6
	v_add_f32_e32 v82, v82, v7
	v_add_f32_e32 v80, v80, v4
	v_add_f32_e32 v82, v82, v5
	s_cselect_b64 vcc, -1, 0
	v_cndmask_b32_e32 v0, 0, v0, vcc
	v_cmp_lt_f32_e32 vcc, 0, v0
	s_cbranch_vccz .LBB0_621
	v_exp_f32_e64 v114, -v0
	s_mov_b64 s[0:1], exec
	v_readlane_b32 s58, v255, 13
	v_readlane_b32 s56, v255, 15
	v_readlane_b32 s30, v255, 19
	v_readlane_b32 s34, v255, 21
	s_and_b64 s[2:3], s[0:1], s[12:13]
	v_readlane_b32 s64, v254, 14
	s_movk_i32 s49, 0x7f
	s_movk_i32 s63, 0x4000
	s_mov_b32 s62, 0x2aaaaaab
	s_movk_i32 s60, 0xff80
	s_movk_i32 s61, 0xa00
	v_readlane_b32 s59, v255, 14
	v_readlane_b32 s57, v255, 16
	v_readlane_b32 s31, v255, 20
	v_readlane_b32 s35, v255, 22
	v_readlane_b32 s6, v255, 23
	v_mov_b32_e32 v231, v219
	v_readlane_b32 s65, v254, 15
	v_readlane_b32 s7, v255, 24
	s_mov_b64 exec, s[2:3]
	s_cbranch_execz .LBB0_500
	ds_write_b32 v243, v114 offset:128
	s_branch .LBB0_500
